# v10
# speedup vs baseline: 1.0051x; 1.0038x over previous
.Lrot_skip:
	s_or_b64 exec, exec, s[18:19]
	v_bfe_u32 v142, v187, 4, 1
	v_mov_b32_e32 v143, 0
	v_mul_u32_u24_e32 v142, 24, v142
	s_mov_b64 s[16:17], 0x1000
	s_mov_b64 s[18:19], 0x2000
	v_lshl_add_u64 v[146:147], v[146:147], 0, v[142:143]
	v_lshl_add_u64 v[168:169], v[146:147], 0, s[16:17]
	v_lshl_add_u64 v[170:171], v[168:169], 0, s[18:19]
	s_mov_b64 s[18:19], 0x200000
	v_lshl_add_u64 v[172:173], v[168:169], 0, s[18:19]
	v_lshl_add_u64 v[174:175], v[170:171], 0, s[18:19]
	s_mov_b64 s[18:19], 0x8000
	v_lshl_add_u64 v[176:177], v[168:169], 0, s[18:19]
	v_lshl_add_u64 v[178:179], v[170:171], 0, s[18:19]
	v_lshl_add_u64 v[180:181], v[172:173], 0, s[18:19]
	v_lshl_add_u64 v[182:183], v[174:175], 0, s[18:19]
	v_cvt_pk_bf16_f32 v124, v124, v125
	v_cvt_pk_bf16_f32 v125, v126, v127
	v_cvt_pk_bf16_f32 v126, v120, v121
	v_cvt_pk_bf16_f32 v127, v122, v123
	v_cvt_pk_bf16_f32 v116, v116, v117
	v_cvt_pk_bf16_f32 v117, v118, v119
	v_cvt_pk_bf16_f32 v118, v112, v113
	v_cvt_pk_bf16_f32 v119, v114, v115
	v_permlane16_swap_b32_e32 v124, v126
	v_permlane16_swap_b32_e32 v125, v127
	global_store_dwordx4 v[168:169], v[124:127], off offset:-4096
	v_cvt_pk_bf16_f32 v108, v108, v109
	v_cvt_pk_bf16_f32 v109, v110, v111
	v_cvt_pk_bf16_f32 v110, v104, v105
	v_cvt_pk_bf16_f32 v111, v106, v107
	v_permlane16_swap_b32_e32 v116, v118
	v_permlane16_swap_b32_e32 v117, v119
	global_store_dwordx4 v[168:169], v[116:119], off
	v_cvt_pk_bf16_f32 v100, v100, v101
	v_cvt_pk_bf16_f32 v101, v102, v103
	v_cvt_pk_bf16_f32 v102, v96, v97
	v_cvt_pk_bf16_f32 v103, v98, v99
	v_permlane16_swap_b32_e32 v108, v110
	v_permlane16_swap_b32_e32 v109, v111
	global_store_dwordx4 v[170:171], v[108:111], off offset:-4096
	v_cvt_pk_bf16_f32 v92, v92, v93
	v_cvt_pk_bf16_f32 v93, v94, v95
	v_cvt_pk_bf16_f32 v94, v88, v89
	v_cvt_pk_bf16_f32 v95, v90, v91
	v_permlane16_swap_b32_e32 v100, v102
	v_permlane16_swap_b32_e32 v101, v103
	global_store_dwordx4 v[170:171], v[100:103], off
	v_cvt_pk_bf16_f32 v84, v84, v85
	v_cvt_pk_bf16_f32 v85, v86, v87
	v_cvt_pk_bf16_f32 v86, v80, v81
	v_cvt_pk_bf16_f32 v87, v82, v83
	v_permlane16_swap_b32_e32 v92, v94
	v_permlane16_swap_b32_e32 v93, v95
	global_store_dwordx4 v[172:173], v[92:95], off offset:-4096
	v_cvt_pk_bf16_f32 v76, v76, v77
	v_cvt_pk_bf16_f32 v77, v78, v79
	v_cvt_pk_bf16_f32 v78, v72, v73
	v_cvt_pk_bf16_f32 v79, v74, v75
	v_permlane16_swap_b32_e32 v84, v86
	v_permlane16_swap_b32_e32 v85, v87
	global_store_dwordx4 v[172:173], v[84:87], off
	v_cvt_pk_bf16_f32 v68, v68, v69
	v_cvt_pk_bf16_f32 v69, v70, v71
	v_cvt_pk_bf16_f32 v70, v64, v65
	v_cvt_pk_bf16_f32 v71, v66, v67
	v_permlane16_swap_b32_e32 v76, v78
	v_permlane16_swap_b32_e32 v77, v79
	global_store_dwordx4 v[174:175], v[76:79], off offset:-4096
	v_cvt_pk_bf16_f32 v60, v60, v61
	v_cvt_pk_bf16_f32 v61, v62, v63
	v_cvt_pk_bf16_f32 v62, v56, v57
	v_cvt_pk_bf16_f32 v63, v58, v59
	v_permlane16_swap_b32_e32 v68, v70
	v_permlane16_swap_b32_e32 v69, v71
	global_store_dwordx4 v[174:175], v[68:71], off
	v_cvt_pk_bf16_f32 v52, v52, v53
	v_cvt_pk_bf16_f32 v53, v54, v55
	v_cvt_pk_bf16_f32 v54, v48, v49
	v_cvt_pk_bf16_f32 v55, v50, v51
	v_permlane16_swap_b32_e32 v60, v62
	v_permlane16_swap_b32_e32 v61, v63
	global_store_dwordx4 v[176:177], v[60:63], off offset:-4096
	v_cvt_pk_bf16_f32 v44, v44, v45
	v_cvt_pk_bf16_f32 v45, v46, v47
	v_cvt_pk_bf16_f32 v46, v40, v41
	v_cvt_pk_bf16_f32 v47, v42, v43
	v_permlane16_swap_b32_e32 v52, v54
	v_permlane16_swap_b32_e32 v53, v55
	global_store_dwordx4 v[176:177], v[52:55], off
	v_cvt_pk_bf16_f32 v36, v36, v37
	v_cvt_pk_bf16_f32 v37, v38, v39
	v_cvt_pk_bf16_f32 v38, v32, v33
	v_cvt_pk_bf16_f32 v39, v34, v35
	v_permlane16_swap_b32_e32 v44, v46
	v_permlane16_swap_b32_e32 v45, v47
	global_store_dwordx4 v[178:179], v[44:47], off offset:-4096
	v_cvt_pk_bf16_f32 v28, v28, v29
	v_cvt_pk_bf16_f32 v29, v30, v31
	v_cvt_pk_bf16_f32 v30, v24, v25
	v_cvt_pk_bf16_f32 v31, v26, v27
	v_permlane16_swap_b32_e32 v36, v38
	v_permlane16_swap_b32_e32 v37, v39
	global_store_dwordx4 v[178:179], v[36:39], off
	v_cvt_pk_bf16_f32 v20, v20, v21
	v_cvt_pk_bf16_f32 v21, v22, v23
	v_cvt_pk_bf16_f32 v22, v16, v17
	v_cvt_pk_bf16_f32 v23, v18, v19
	v_permlane16_swap_b32_e32 v28, v30
	v_permlane16_swap_b32_e32 v29, v31
	global_store_dwordx4 v[180:181], v[28:31], off offset:-4096
	v_cvt_pk_bf16_f32 v12, v12, v13
	v_cvt_pk_bf16_f32 v13, v14, v15
	v_cvt_pk_bf16_f32 v14, v8, v9
	v_cvt_pk_bf16_f32 v15, v10, v11
	v_permlane16_swap_b32_e32 v20, v22
	v_permlane16_swap_b32_e32 v21, v23
	global_store_dwordx4 v[180:181], v[20:23], off
	v_cvt_pk_bf16_f32 v4, v4, v5
	v_cvt_pk_bf16_f32 v5, v6, v7
	v_cvt_pk_bf16_f32 v6, v0, v1
	v_cvt_pk_bf16_f32 v7, v2, v3
	v_permlane16_swap_b32_e32 v12, v14
	v_permlane16_swap_b32_e32 v13, v15
	global_store_dwordx4 v[182:183], v[12:15], off offset:-4096
	s_nop 1
	v_permlane16_swap_b32_e32 v4, v6
	v_permlane16_swap_b32_e32 v5, v7
	global_store_dwordx4 v[182:183], v[4:7], off
	s_mov_b32 s2, s14
	s_mov_b32 s0, s12
	s_andn2_b64 vcc, exec, s[10:11]
	s_waitcnt vmcnt(38)
	s_cbranch_vccz .LBB0_148
	s_branch .Lseam_qkvrot

.LBB0_193:
	ds_read_b128 v[64:67], v180 offset:49152
	ds_read_b128 v[68:71], v180 offset:57344
	ds_read_b128 v[128:131], v179 offset:49152
	s_waitcnt vmcnt(2)
	ds_read_b128 v[132:135], v179 offset:57344
	ds_read_b128 v[248:251], v165 offset:49152
	ds_read_b128 v[252:255], v165 offset:57344
	s_waitcnt vmcnt(1)
	v_exp_f32_e32 v136, v144
	v_add_f32_e32 v144, 0, v216
	s_waitcnt lgkmcnt(5)
	v_mfma_f32_32x32x16_bf16 v[80:95], v[64:67], v[124:127], 0
	v_add_f32_e32 v144, v219, v144
	v_add_f32_e32 v144, v213, v144
	v_add_f32_e32 v144, v217, v144
	v_add_f32_e32 v144, v212, v144
	v_add_f32_e32 v144, v214, v144
	v_add_f32_e32 v144, v210, v144
	v_add_f32_e32 v144, v211, v144
	s_waitcnt lgkmcnt(4)
	v_mfma_f32_32x32x16_bf16 v[64:79], v[68:71], v[124:127], 0
	v_add_f32_e32 v144, v207, v144
	v_add_f32_e32 v144, v209, v144
	v_add_f32_e32 v144, v206, v144
	v_add_f32_e32 v144, v208, v144
	v_add_f32_e32 v144, v195, v144
	v_add_f32_e32 v144, v197, v144
	v_add_f32_e32 v144, v194, v144
	s_waitcnt lgkmcnt(3)
	v_mfma_f32_32x32x16_bf16 v[80:95], v[128:131], v[120:123], v[80:95]
	v_add_f32_e32 v144, v196, v144
	v_exp_f32_e32 v137, v145
	v_exp_f32_e32 v138, v158
	v_exp_f32_e32 v139, v159
	s_waitcnt vmcnt(0)
	v_exp_f32_e32 v140, v152
	v_exp_f32_e32 v141, v153
	v_exp_f32_e32 v142, v146
	s_waitcnt lgkmcnt(2)
	v_mfma_f32_32x32x16_bf16 v[64:79], v[132:135], v[120:123], v[64:79]
	ds_read_b128 v[128:131], v163 offset:49152
	ds_read_b128 v[132:135], v163 offset:57344
	v_exp_f32_e32 v143, v147
	s_sub_i32 s0, s26, 63
	s_waitcnt lgkmcnt(3)
	v_mfma_f32_32x32x16_bf16 v[80:95], v[248:251], v[116:119], v[80:95]
	s_waitcnt lgkmcnt(2)
	v_mfma_f32_32x32x16_bf16 v[64:79], v[252:255], v[116:119], v[64:79]
	ds_read_b128 v[248:251], v180 offset:49280
	ds_read_b128 v[252:255], v180 offset:57472
	s_waitcnt lgkmcnt(3)
	v_mfma_f32_32x32x16_bf16 v[80:95], v[128:131], v[112:115], v[80:95]
	s_waitcnt lgkmcnt(2)
	v_mfma_f32_32x32x16_bf16 v[64:79], v[132:135], v[112:115], v[64:79]
	ds_read_b128 v[128:131], v179 offset:49280
	ds_read_b128 v[132:135], v179 offset:57472
	s_waitcnt lgkmcnt(3)
	v_mfma_f32_32x32x16_bf16 v[80:95], v[248:251], v[108:111], v[80:95]
	s_waitcnt lgkmcnt(2)
	v_mfma_f32_32x32x16_bf16 v[64:79], v[252:255], v[108:111], v[64:79]
	ds_read_b128 v[248:251], v165 offset:49280
	ds_read_b128 v[252:255], v165 offset:57472
	s_waitcnt lgkmcnt(3)
	v_mfma_f32_32x32x16_bf16 v[80:95], v[128:131], v[104:107], v[80:95]
	s_waitcnt lgkmcnt(2)
	v_mfma_f32_32x32x16_bf16 v[64:79], v[132:135], v[104:107], v[64:79]
	ds_read_b128 v[128:131], v163 offset:49280
	ds_read_b128 v[132:135], v163 offset:57472
	s_waitcnt lgkmcnt(3)
	v_mfma_f32_32x32x16_bf16 v[80:95], v[248:251], v[100:103], v[80:95]
	s_waitcnt lgkmcnt(2)
	v_mfma_f32_32x32x16_bf16 v[64:79], v[252:255], v[100:103], v[64:79]
	s_waitcnt lgkmcnt(1)
	v_mfma_f32_32x32x16_bf16 v[80:95], v[128:131], v[96:99], v[80:95]
	v_exp_f32_e32 v128, v156
	v_exp_f32_e32 v129, v157
	v_exp_f32_e32 v130, v154
	v_exp_f32_e32 v131, v155
	v_add_f32_e32 v144, v128, v144
	v_add_f32_e32 v144, v129, v144
	v_add_f32_e32 v144, v130, v144
	s_waitcnt lgkmcnt(0)
	v_mfma_f32_32x32x16_bf16 v[64:79], v[132:135], v[96:99], v[64:79]
	v_exp_f32_e32 v132, v150
	v_exp_f32_e32 v133, v151
	v_exp_f32_e32 v134, v148
	v_exp_f32_e32 v135, v149
	v_add_f32_e32 v144, v131, v144
	v_add_f32_e32 v144, v132, v144
	v_add_f32_e32 v144, v133, v144
	v_add_f32_e32 v144, v134, v144
	v_add_f32_e32 v144, v135, v144
	v_add_f32_e32 v144, v136, v144
	v_add_f32_e32 v144, v137, v144
	v_add_f32_e32 v144, v138, v144
	v_add_f32_e32 v144, v139, v144
	v_add_f32_e32 v144, v140, v144
	v_add_f32_e32 v144, v141, v144
	v_add_f32_e32 v144, v142, v144
	v_add_f32_e32 v190, v143, v144
	v_mov_b32_e32 v191, v190
	s_nop 1
	v_permlane32_swap_b32_e32 v190, v191
	s_nop 0
	v_cvt_pk_bf16_f32 v144, v216, v219
	s_nop 0
	v_cvt_pk_bf16_f32 v145, v213, v217
	s_nop 0
	v_cvt_pk_bf16_f32 v146, v212, v214
	s_nop 0
	v_cvt_pk_bf16_f32 v147, v210, v211
	s_nop 0
	v_cvt_pk_bf16_f32 v148, v207, v209
	s_nop 0
	v_cvt_pk_bf16_f32 v149, v206, v208
	s_nop 0
	v_cvt_pk_bf16_f32 v150, v195, v197
	s_nop 0
	v_cvt_pk_bf16_f32 v151, v194, v196
	s_nop 0
	v_cvt_pk_bf16_f32 v152, v128, v129
	s_nop 0
	v_cvt_pk_bf16_f32 v153, v130, v131
	s_nop 0
	v_cvt_pk_bf16_f32 v154, v132, v133
	s_nop 0
	v_cvt_pk_bf16_f32 v155, v134, v135
	s_nop 0
	v_cvt_pk_bf16_f32 v156, v136, v137
	s_nop 0
	v_cvt_pk_bf16_f32 v157, v138, v139
	s_nop 0
	v_cvt_pk_bf16_f32 v158, v140, v141
	s_nop 0
	v_cvt_pk_bf16_f32 v159, v142, v143
	s_nop 0
	v_permlane32_swap_b32_e32 v144, v146
	v_permlane32_swap_b32_e32 v145, v147
	v_permlane32_swap_b32_e32 v148, v150
	v_permlane32_swap_b32_e32 v149, v151
	v_permlane32_swap_b32_e32 v152, v154
	v_permlane32_swap_b32_e32 v153, v155
	v_permlane32_swap_b32_e32 v156, v158
	v_permlane32_swap_b32_e32 v157, v159
	v_add_u32_e32 v192, s26, v160
	v_add_u32_e32 v128, 1, v192
	v_add_u32_e32 v130, 33, v192
	v_ashrrev_i32_e32 v129, 31, v128
	v_ashrrev_i32_e32 v131, 31, v130
	v_lshlrev_b64 v[136:137], 8, v[128:129]
	v_lshlrev_b64 v[138:139], 8, v[130:131]
	v_lshl_add_u64 v[128:129], v[166:167], 0, v[136:137]
	v_lshl_add_u64 v[132:133], v[166:167], 0, v[138:139]
	v_lshl_add_u64 v[136:137], v[168:169], 0, v[136:137]
	v_lshl_add_u64 v[140:141], v[168:169], 0, v[138:139]
	global_load_dwordx4 v[128:131], v[128:129], off
	s_nop 0
	global_load_dwordx4 v[132:135], v[132:133], off
	s_nop 0
	global_load_dwordx4 v[136:139], v[136:137], off
	s_nop 0
	global_load_dwordx4 v[140:143], v[140:141], off
	ds_read_b64_tr_b16 v[194:195], v173 offset:0
	ds_read_b64_tr_b16 v[196:197], v173 offset:0x800
	ds_read_b64_tr_b16 v[206:207], v173 offset:0x1000
	ds_read_b64_tr_b16 v[208:209], v173 offset:0x1800
	ds_read_b64_tr_b16 v[210:211], v173 offset:0x2000
	ds_read_b64_tr_b16 v[212:213], v173 offset:0x2800
	ds_read_b64_tr_b16 v[214:215], v173 offset:0x3000
	ds_read_b64_tr_b16 v[216:217], v173 offset:0x3800
	s_waitcnt lgkmcnt(0)
	s_nop 0
	v_mfma_f32_32x32x16_bf16 v[48:63], v[144:147], v[194:197], v[48:63]
	ds_read_b64_tr_b16 v[194:195], v173 offset:0x200
	ds_read_b64_tr_b16 v[196:197], v173 offset:0xa00
	v_mfma_f32_32x32x16_bf16 v[48:63], v[148:151], v[206:209], v[48:63]
	ds_read_b64_tr_b16 v[206:207], v173 offset:0x1200
	ds_read_b64_tr_b16 v[208:209], v173 offset:0x1a00
	v_mfma_f32_32x32x16_bf16 v[48:63], v[152:155], v[210:213], v[48:63]
	ds_read_b64_tr_b16 v[210:211], v173 offset:0x2200
	ds_read_b64_tr_b16 v[212:213], v173 offset:0x2a00
	v_mfma_f32_32x32x16_bf16 v[48:63], v[156:159], v[214:217], v[48:63]
	ds_read_b64_tr_b16 v[214:215], v173 offset:0x3200
	ds_read_b64_tr_b16 v[216:217], v173 offset:0x3a00
	s_waitcnt lgkmcnt(0)
	v_mfma_f32_32x32x16_bf16 v[32:47], v[144:147], v[194:197], v[32:47]
	ds_read_b64_tr_b16 v[194:195], v173 offset:0x400
	ds_read_b64_tr_b16 v[196:197], v173 offset:0xc00
	v_mfma_f32_32x32x16_bf16 v[32:47], v[148:151], v[206:209], v[32:47]
	ds_read_b64_tr_b16 v[206:207], v173 offset:0x1400
	ds_read_b64_tr_b16 v[208:209], v173 offset:0x1c00
	v_mfma_f32_32x32x16_bf16 v[32:47], v[152:155], v[210:213], v[32:47]
	ds_read_b64_tr_b16 v[210:211], v173 offset:0x2400
	ds_read_b64_tr_b16 v[212:213], v173 offset:0x2c00
	v_mfma_f32_32x32x16_bf16 v[32:47], v[156:159], v[214:217], v[32:47]
	ds_read_b64_tr_b16 v[214:215], v173 offset:0x3400
	ds_read_b64_tr_b16 v[216:217], v173 offset:0x3c00
	s_waitcnt lgkmcnt(0)
	v_mfma_f32_32x32x16_bf16 v[16:31], v[144:147], v[194:197], v[16:31]
	ds_read_b64_tr_b16 v[194:195], v173 offset:0x600
	ds_read_b64_tr_b16 v[196:197], v173 offset:0xe00
	v_mfma_f32_32x32x16_bf16 v[16:31], v[148:151], v[206:209], v[16:31]
	ds_read_b64_tr_b16 v[206:207], v173 offset:0x1600
	ds_read_b64_tr_b16 v[208:209], v173 offset:0x1e00
	v_mfma_f32_32x32x16_bf16 v[16:31], v[152:155], v[210:213], v[16:31]
	ds_read_b64_tr_b16 v[210:211], v173 offset:0x2600
	ds_read_b64_tr_b16 v[212:213], v173 offset:0x2e00
	v_mfma_f32_32x32x16_bf16 v[16:31], v[156:159], v[214:217], v[16:31]
	ds_read_b64_tr_b16 v[214:215], v173 offset:0x3600
	ds_read_b64_tr_b16 v[216:217], v173 offset:0x3e00
	s_waitcnt lgkmcnt(0)
	v_mfma_f32_32x32x16_bf16 v[0:15], v[144:147], v[194:197], v[0:15]
	s_cmp_le_i32 s26, s19
	s_cselect_b64 s[2:3], -1, 0
	s_cmp_gt_i32 s0, s24
	s_cselect_b64 s[0:1], -1, 0
	s_and_b64 s[0:1], s[2:3], s[0:1]
	s_and_b64 vcc, exec, s[0:1]
	v_mfma_f32_32x32x16_bf16 v[0:15], v[148:151], v[206:209], v[0:15]
	v_mfma_f32_32x32x16_bf16 v[0:15], v[152:155], v[210:213], v[0:15]
	v_mfma_f32_32x32x16_bf16 v[0:15], v[156:159], v[214:217], v[0:15]
	s_cbranch_vccnz .LBB0_195
	v_add_u32_e32 v144, 0x207b, v188
	v_cmp_gt_u32_e32 vcc, s73, v144
	v_add_u32_e32 v144, 0x5b, v188
	s_nop 0
	v_cndmask_b32_e32 v80, v202, v80, vcc
	v_cmp_lt_u32_e32 vcc, s95, v144
	v_add_u32_e32 v144, 0x7a, v188
	s_nop 0
	v_cndmask_b32_e32 v64, v202, v64, vcc
	v_cmp_lt_u32_e32 vcc, s95, v144
	v_add_u32_e32 v144, 0x5a, v188
	s_nop 0
	v_cndmask_b32_e32 v81, v202, v81, vcc
	v_cmp_lt_u32_e32 vcc, s95, v144
	v_add_u32_e32 v144, 0x79, v188
	s_nop 0
	v_cndmask_b32_e32 v65, v202, v65, vcc
	v_cmp_lt_u32_e32 vcc, s95, v144
	v_add_u32_e32 v144, 0x59, v188
	s_nop 0
	v_cndmask_b32_e32 v82, v202, v82, vcc
	v_cmp_lt_u32_e32 vcc, s95, v144
	v_add_u32_e32 v144, 0x78, v188
	s_nop 0
	v_cndmask_b32_e32 v66, v202, v66, vcc
	v_cmp_lt_u32_e32 vcc, s95, v144
	v_add_u32_e32 v144, 0x58, v188
	s_nop 0
	v_cndmask_b32_e32 v83, v202, v83, vcc
	v_cmp_lt_u32_e32 vcc, s95, v144
	v_add_u32_e32 v144, 0x73, v188
	s_nop 0
	v_cndmask_b32_e32 v67, v202, v67, vcc
	v_cmp_lt_u32_e32 vcc, s95, v144
	v_add_u32_e32 v144, 0x53, v188
	s_nop 0
	v_cndmask_b32_e32 v84, v202, v84, vcc
	v_cmp_lt_u32_e32 vcc, s95, v144
	v_add_u32_e32 v144, 0x72, v188
	s_nop 0
	v_cndmask_b32_e32 v68, v202, v68, vcc
	v_cmp_lt_u32_e32 vcc, s95, v144
	v_add_u32_e32 v144, 0x52, v188
	s_nop 0
	v_cndmask_b32_e32 v85, v202, v85, vcc
	v_cmp_lt_u32_e32 vcc, s95, v144
	v_add_u32_e32 v144, 0x71, v188
	s_nop 0
	v_cndmask_b32_e32 v69, v202, v69, vcc
	v_cmp_lt_u32_e32 vcc, s95, v144
	v_add_u32_e32 v144, 0x51, v188
	s_nop 0
	v_cndmask_b32_e32 v86, v202, v86, vcc
	v_cmp_lt_u32_e32 vcc, s95, v144
	v_add_u32_e32 v144, 0x70, v188
	s_nop 0
	v_cndmask_b32_e32 v70, v202, v70, vcc
	v_cmp_lt_u32_e32 vcc, s95, v144
	v_add_u32_e32 v144, 0x50, v188
	s_nop 0
	v_cndmask_b32_e32 v87, v202, v87, vcc
	v_cmp_lt_u32_e32 vcc, s95, v144
	v_add_u32_e32 v144, 0x6b, v188
	s_nop 0
	v_cndmask_b32_e32 v71, v202, v71, vcc
	v_cmp_lt_u32_e32 vcc, s95, v144
	v_add_u32_e32 v144, 0x4b, v188
	s_nop 0
	v_cndmask_b32_e32 v88, v202, v88, vcc
	v_cmp_lt_u32_e32 vcc, s95, v144
	v_add_u32_e32 v144, 0x6a, v188
	s_nop 0
	v_cndmask_b32_e32 v72, v202, v72, vcc
	v_cmp_lt_u32_e32 vcc, s95, v144
	v_add_u32_e32 v144, 0x4a, v188
	s_nop 0
	v_cndmask_b32_e32 v89, v202, v89, vcc
	v_cmp_lt_u32_e32 vcc, s95, v144
	v_add_u32_e32 v144, 0x69, v188
	s_nop 0
	v_cndmask_b32_e32 v73, v202, v73, vcc
	v_cmp_lt_u32_e32 vcc, s95, v144
	v_add_u32_e32 v144, 0x49, v188
	s_nop 0
	v_cndmask_b32_e32 v90, v202, v90, vcc
	v_cmp_lt_u32_e32 vcc, s95, v144
	v_add_u32_e32 v144, 0x68, v188
	s_nop 0
	v_cndmask_b32_e32 v74, v202, v74, vcc
	v_cmp_lt_u32_e32 vcc, s95, v144
	v_add_u32_e32 v144, 0x48, v188
	s_nop 0
	v_cndmask_b32_e32 v91, v202, v91, vcc
	v_cmp_lt_u32_e32 vcc, s95, v144
	v_add_u32_e32 v144, 0x63, v188
	s_nop 0
	v_cndmask_b32_e32 v75, v202, v75, vcc
	v_cmp_lt_u32_e32 vcc, s95, v144
	v_add_u32_e32 v144, 0x43, v188
	s_nop 0
	v_cndmask_b32_e32 v92, v202, v92, vcc
	v_cmp_lt_u32_e32 vcc, s95, v144
	v_add_u32_e32 v144, 0x62, v188
	s_nop 0
	v_cndmask_b32_e32 v76, v202, v76, vcc
	v_cmp_lt_u32_e32 vcc, s95, v144
	v_add_u32_e32 v144, 0x42, v188
	s_nop 0
	v_cndmask_b32_e32 v93, v202, v93, vcc
	v_cmp_lt_u32_e32 vcc, s95, v144
	v_add_u32_e32 v144, 0x61, v188
	s_nop 0
	v_cndmask_b32_e32 v77, v202, v77, vcc
	v_cmp_lt_u32_e32 vcc, s95, v144
	v_add_u32_e32 v144, 0x41, v188
	s_nop 0
	v_cndmask_b32_e32 v94, v202, v94, vcc
	v_cmp_lt_u32_e32 vcc, s95, v144
	v_add_u32_e32 v144, 0x60, v188
	s_nop 0
	v_cndmask_b32_e32 v78, v202, v78, vcc
	v_cmp_lt_u32_e32 vcc, s95, v144
	v_add_u32_e32 v144, 64, v188
	s_nop 0
	v_cndmask_b32_e32 v95, v202, v95, vcc
	v_cmp_lt_u32_e32 vcc, s95, v144
	s_nop 1
	v_cndmask_b32_e32 v79, v202, v79, vcc

.LBB0_199:
	v_cndmask_b32_e64 v186, v144, v186, s[0:1]
	v_mul_f32_e32 v194, 0xbe0293ee, v186
	v_fmamk_f32 v80, v80, 0x3e0293ee, v194
	v_fmamk_f32 v81, v81, 0x3e0293ee, v194
	v_fmamk_f32 v82, v82, 0x3e0293ee, v194
	v_fmamk_f32 v83, v83, 0x3e0293ee, v194
	v_fmamk_f32 v84, v84, 0x3e0293ee, v194
	v_fmamk_f32 v85, v85, 0x3e0293ee, v194
	v_fmamk_f32 v86, v86, 0x3e0293ee, v194
	v_fmamk_f32 v87, v87, 0x3e0293ee, v194
	v_fmamk_f32 v88, v88, 0x3e0293ee, v194
	v_fmamk_f32 v89, v89, 0x3e0293ee, v194
	v_fmamk_f32 v90, v90, 0x3e0293ee, v194
	v_fmamk_f32 v91, v91, 0x3e0293ee, v194
	v_fmamk_f32 v92, v92, 0x3e0293ee, v194
	v_fmamk_f32 v93, v93, 0x3e0293ee, v194
	v_fmamk_f32 v94, v94, 0x3e0293ee, v194
	v_fmamk_f32 v95, v95, 0x3e0293ee, v194
	v_exp_f32_e32 v144, v80
	v_exp_f32_e32 v159, v81
	v_exp_f32_e32 v145, v82
	v_exp_f32_e32 v158, v83
	v_exp_f32_e32 v146, v84
	v_exp_f32_e32 v157, v85
	v_exp_f32_e32 v147, v86
	v_exp_f32_e32 v156, v87
	v_exp_f32_e32 v148, v88
	v_exp_f32_e32 v155, v89
	v_exp_f32_e32 v149, v90
	v_exp_f32_e32 v154, v91
	v_exp_f32_e32 v150, v92
	v_exp_f32_e32 v153, v93
	v_exp_f32_e32 v151, v94
	v_exp_f32_e32 v152, v95
	v_fmamk_f32 v215, v68, 0x3e0293ee, v194
	v_fmamk_f32 v211, v64, 0x3e0293ee, v194
	v_fmamk_f32 v212, v65, 0x3e0293ee, v194
	v_fmamk_f32 v213, v66, 0x3e0293ee, v194
	v_fmamk_f32 v214, v67, 0x3e0293ee, v194
	v_fmamk_f32 v196, v69, 0x3e0293ee, v194
	v_fmamk_f32 v197, v70, 0x3e0293ee, v194
	v_fmamk_f32 v206, v71, 0x3e0293ee, v194
	v_fmamk_f32 v207, v72, 0x3e0293ee, v194
	v_fmamk_f32 v208, v73, 0x3e0293ee, v194
	v_fmamk_f32 v209, v74, 0x3e0293ee, v194
	v_fmamk_f32 v210, v75, 0x3e0293ee, v194
	v_fmamk_f32 v195, v76, 0x3e0293ee, v194
	v_fmamk_f32 v216, v77, 0x3e0293ee, v194
	v_fmamk_f32 v217, v78, 0x3e0293ee, v194
	v_fmac_f32_e32 v194, 0x3e0293ee, v79
	s_waitcnt lgkmcnt(0)
	s_barrier
	ds_read_b128 v[64:67], v180 offset:32768
	ds_read_b128 v[68:71], v180 offset:40960
	ds_read_b128 v[218:221], v179 offset:32768
	ds_read_b128 v[222:225], v179 offset:40960
	ds_read_b128 v[248:251], v165 offset:32768
	ds_read_b128 v[252:255], v165 offset:40960
	v_exp_f32_e32 v211, v211
	v_exp_f32_e32 v212, v212
	s_waitcnt lgkmcnt(5)
	v_mfma_f32_32x32x16_bf16 v[80:95], v[64:67], v[124:127], 0
	v_exp_f32_e32 v213, v213
	v_exp_f32_e32 v214, v214
	v_exp_f32_e32 v196, v196
	v_exp_f32_e32 v197, v197
	v_exp_f32_e32 v206, v206
	v_exp_f32_e32 v207, v207
	v_exp_f32_e32 v208, v208
	s_waitcnt lgkmcnt(4)
	v_mfma_f32_32x32x16_bf16 v[64:79], v[68:71], v[124:127], 0
	v_exp_f32_e32 v209, v209
	v_exp_f32_e32 v210, v210
	v_exp_f32_e32 v195, v195
	v_exp_f32_e32 v216, v216
	v_exp_f32_e32 v217, v217
	v_exp_f32_e32 v194, v194
	s_waitcnt lgkmcnt(3)
	v_mfma_f32_32x32x16_bf16 v[80:95], v[218:221], v[120:123], v[80:95]
	s_waitcnt lgkmcnt(2)
	v_mfma_f32_32x32x16_bf16 v[64:79], v[222:225], v[120:123], v[64:79]
	ds_read_b128 v[218:221], v163 offset:32768
	ds_read_b128 v[222:225], v163 offset:40960
	s_waitcnt lgkmcnt(3)
	v_mfma_f32_32x32x16_bf16 v[80:95], v[248:251], v[116:119], v[80:95]
	s_waitcnt lgkmcnt(2)
	v_mfma_f32_32x32x16_bf16 v[64:79], v[252:255], v[116:119], v[64:79]
	ds_read_b128 v[248:251], v180 offset:32896
	ds_read_b128 v[252:255], v180 offset:41088
	s_waitcnt lgkmcnt(3)
	v_mfma_f32_32x32x16_bf16 v[80:95], v[218:221], v[112:115], v[80:95]
	s_waitcnt lgkmcnt(2)
	v_mfma_f32_32x32x16_bf16 v[64:79], v[222:225], v[112:115], v[64:79]
	ds_read_b128 v[218:221], v179 offset:32896
	ds_read_b128 v[222:225], v179 offset:41088
	s_waitcnt lgkmcnt(3)
	v_mfma_f32_32x32x16_bf16 v[80:95], v[248:251], v[108:111], v[80:95]
	s_waitcnt lgkmcnt(2)
	v_mfma_f32_32x32x16_bf16 v[64:79], v[252:255], v[108:111], v[64:79]
	ds_read_b128 v[248:251], v165 offset:32896
	ds_read_b128 v[252:255], v165 offset:41088
	s_waitcnt lgkmcnt(3)
	v_mfma_f32_32x32x16_bf16 v[80:95], v[218:221], v[104:107], v[80:95]
	s_waitcnt lgkmcnt(2)
	v_mfma_f32_32x32x16_bf16 v[64:79], v[222:225], v[104:107], v[64:79]
	ds_read_b128 v[218:221], v163 offset:32896
	ds_read_b128 v[222:225], v163 offset:41088
	s_waitcnt lgkmcnt(3)
	v_mfma_f32_32x32x16_bf16 v[80:95], v[248:251], v[100:103], v[80:95]
	s_waitcnt lgkmcnt(2)
	v_mfma_f32_32x32x16_bf16 v[64:79], v[252:255], v[100:103], v[64:79]
	s_waitcnt lgkmcnt(1)
	v_mfma_f32_32x32x16_bf16 v[80:95], v[218:221], v[96:99], v[80:95]
	v_exp_f32_e32 v219, v215
	v_add_f32_e32 v215, 0, v144
	v_add_f32_e32 v215, v159, v215
	v_add_f32_e32 v215, v145, v215
	v_add_f32_e32 v215, v158, v215
	v_add_f32_e32 v215, v146, v215
	v_add_f32_e32 v215, v157, v215
	v_add_f32_e32 v215, v147, v215
	v_add_f32_e32 v215, v156, v215
	v_add_f32_e32 v215, v148, v215
	v_add_f32_e32 v215, v155, v215
	v_add_f32_e32 v215, v149, v215
	v_add_f32_e32 v215, v154, v215
	v_add_f32_e32 v215, v150, v215
	v_add_f32_e32 v215, v153, v215
	v_add_f32_e32 v215, v151, v215
	v_add_f32_e32 v215, v152, v215
	v_add_f32_e32 v215, v211, v215
	v_add_f32_e32 v215, v212, v215
	v_add_f32_e32 v215, v213, v215
	v_add_f32_e32 v215, v214, v215
	v_add_f32_e32 v215, v219, v215
	v_add_f32_e32 v215, v196, v215
	v_add_f32_e32 v215, v197, v215
	v_add_f32_e32 v215, v206, v215
	v_add_f32_e32 v215, v207, v215
	v_add_f32_e32 v215, v208, v215
	s_waitcnt lgkmcnt(0)
	v_mfma_f32_32x32x16_bf16 v[64:79], v[222:225], v[96:99], v[64:79]
	v_add_f32_e32 v215, v209, v215
	v_add_f32_e32 v215, v210, v215
	v_add_f32_e32 v215, v195, v215
	v_add_f32_e32 v215, v216, v215
	v_add_f32_e32 v215, v217, v215
	v_add_f32_e32 v215, v194, v215
	v_mov_b32_e32 v218, v215
	s_nop 0
	v_cvt_pk_bf16_f32 v144, v144, v159
	s_nop 0
	v_cvt_pk_bf16_f32 v145, v145, v158
	s_nop 0
	v_cvt_pk_bf16_f32 v146, v146, v157
	s_nop 0
	v_cvt_pk_bf16_f32 v147, v147, v156
	s_nop 0
	v_cvt_pk_bf16_f32 v148, v148, v155
	s_nop 0
	v_cvt_pk_bf16_f32 v149, v149, v154
	s_nop 0
	v_cvt_pk_bf16_f32 v150, v150, v153
	s_nop 0
	v_cvt_pk_bf16_f32 v151, v151, v152
	s_nop 0
	v_cvt_pk_bf16_f32 v152, v211, v212
	s_nop 0
	v_cvt_pk_bf16_f32 v153, v213, v214
	s_nop 0
	v_cvt_pk_bf16_f32 v154, v219, v196
	s_nop 0
	v_cvt_pk_bf16_f32 v155, v197, v206
	s_nop 0
	v_cvt_pk_bf16_f32 v156, v207, v208
	s_nop 0
	v_cvt_pk_bf16_f32 v157, v209, v210
	s_nop 0
	v_cvt_pk_bf16_f32 v158, v195, v216
	s_nop 0
	v_cvt_pk_bf16_f32 v159, v217, v194
	s_nop 1
	v_permlane32_swap_b32_e32 v215, v218
	v_permlane32_swap_b32_e32 v144, v146
	v_permlane32_swap_b32_e32 v145, v147
	v_permlane32_swap_b32_e32 v148, v150
	v_permlane32_swap_b32_e32 v149, v151
	v_permlane32_swap_b32_e32 v152, v154
	v_permlane32_swap_b32_e32 v153, v155
	v_permlane32_swap_b32_e32 v156, v158
	v_permlane32_swap_b32_e32 v157, v159
	s_add_i32 s0, s25, 1
	s_cmp_lt_u32 s0, s23
	s_cselect_b64 s[2:3], -1, 0
	s_cmp_ge_u32 s0, s23
	s_cbranch_scc1 .LBB0_201
	v_add_u32_e32 v128, 0x41, v192
	v_add_u32_e32 v130, 0x61, v192
	v_ashrrev_i32_e32 v129, 31, v128
	v_ashrrev_i32_e32 v131, 31, v130
	v_lshlrev_b64 v[136:137], 8, v[128:129]
	v_lshlrev_b64 v[138:139], 8, v[130:131]
	v_lshl_add_u64 v[128:129], v[166:167], 0, v[136:137]
	v_lshl_add_u64 v[132:133], v[166:167], 0, v[138:139]
	v_lshl_add_u64 v[136:137], v[168:169], 0, v[136:137]
	v_lshl_add_u64 v[140:141], v[168:169], 0, v[138:139]
	global_load_dwordx4 v[128:131], v[128:129], off
	s_nop 0
	global_load_dwordx4 v[132:135], v[132:133], off
	s_nop 0
	global_load_dwordx4 v[136:139], v[136:137], off
	s_nop 0
	global_load_dwordx4 v[140:143], v[140:141], off

.LBB0_426:
	v_add_u32_e32 v182, s10, v153
	v_or_b32_e32 v183, s12, v128
	s_mov_b32 s10, s2
	v_bfe_u32 v238, v187, 4, 1
	v_lshl_add_u32 v182, v182, 11, v183
	v_mul_u32_u24_e32 v238, 24, v238
	v_lshl_add_u32 v132, v182, 1, v238
	v_add_u32_e32 v133, 0x10000, v132
	v_add_u32_e32 v134, 0x20000, v132
	v_add_u32_e32 v135, 0x30000, v132
	v_add_u32_e32 v136, 0x80000, v132
	v_add_u32_e32 v137, 0x90000, v132
	v_add_u32_e32 v138, 0xa0000, v132
	v_add_u32_e32 v139, 0xb0000, v132
	global_load_dwordx4 v[162:165], v132, s[34:35]
	global_load_dwordx4 v[166:169], v133, s[34:35]
	global_load_dwordx4 v[170:173], v134, s[34:35]
	global_load_dwordx4 v[174:177], v135, s[34:35]
	global_load_dwordx4 v[178:181], v132, s[34:35] offset:256
	global_load_dwordx4 v[190:193], v133, s[34:35] offset:256
	global_load_dwordx4 v[194:197], v134, s[34:35] offset:256
	global_load_dwordx4 v[206:209], v135, s[34:35] offset:256
	global_load_dwordx4 v[210:213], v136, s[34:35]
	global_load_dwordx4 v[214:217], v137, s[34:35]
	global_load_dwordx4 v[218:221], v138, s[34:35]
	global_load_dwordx4 v[222:225], v139, s[34:35]
	global_load_dwordx4 v[226:229], v136, s[34:35] offset:256
	global_load_dwordx4 v[230:233], v137, s[34:35] offset:256
	global_load_dwordx4 v[234:237], v138, s[34:35] offset:256
	global_load_dwordx4 v[240:243], v139, s[34:35] offset:256
	v_permlane16_swap_b32_e32 v124, v120
	v_permlane16_swap_b32_e32 v125, v121
	v_permlane16_swap_b32_e32 v126, v122
	v_permlane16_swap_b32_e32 v127, v123
	v_permlane16_swap_b32_e32 v116, v112
	v_permlane16_swap_b32_e32 v117, v113
	v_permlane16_swap_b32_e32 v118, v114
	v_permlane16_swap_b32_e32 v119, v115
	v_permlane16_swap_b32_e32 v108, v104
	v_permlane16_swap_b32_e32 v109, v105
	v_permlane16_swap_b32_e32 v110, v106
	v_permlane16_swap_b32_e32 v111, v107
	v_permlane16_swap_b32_e32 v100, v96
	v_permlane16_swap_b32_e32 v101, v97
	v_permlane16_swap_b32_e32 v102, v98
	v_permlane16_swap_b32_e32 v103, v99
	v_permlane16_swap_b32_e32 v92, v88
	v_permlane16_swap_b32_e32 v93, v89
	v_permlane16_swap_b32_e32 v94, v90
	v_permlane16_swap_b32_e32 v95, v91
	v_permlane16_swap_b32_e32 v84, v80
	v_permlane16_swap_b32_e32 v85, v81
	v_permlane16_swap_b32_e32 v86, v82
	v_permlane16_swap_b32_e32 v87, v83
	v_permlane16_swap_b32_e32 v76, v72
	v_permlane16_swap_b32_e32 v77, v73
	v_permlane16_swap_b32_e32 v78, v74
	v_permlane16_swap_b32_e32 v79, v75
	v_permlane16_swap_b32_e32 v68, v64
	v_permlane16_swap_b32_e32 v69, v65
	v_permlane16_swap_b32_e32 v70, v66
	v_permlane16_swap_b32_e32 v71, v67
	v_permlane16_swap_b32_e32 v60, v56
	v_permlane16_swap_b32_e32 v61, v57
	v_permlane16_swap_b32_e32 v62, v58
	v_permlane16_swap_b32_e32 v63, v59
	v_permlane16_swap_b32_e32 v52, v48
	v_permlane16_swap_b32_e32 v53, v49
	v_permlane16_swap_b32_e32 v54, v50
	v_permlane16_swap_b32_e32 v55, v51
	v_permlane16_swap_b32_e32 v44, v40
	v_permlane16_swap_b32_e32 v45, v41
	v_permlane16_swap_b32_e32 v46, v42
	v_permlane16_swap_b32_e32 v47, v43
	v_permlane16_swap_b32_e32 v36, v32
	v_permlane16_swap_b32_e32 v37, v33
	v_permlane16_swap_b32_e32 v38, v34
	v_permlane16_swap_b32_e32 v39, v35
	v_permlane16_swap_b32_e32 v28, v24
	v_permlane16_swap_b32_e32 v29, v25
	v_permlane16_swap_b32_e32 v30, v26
	v_permlane16_swap_b32_e32 v31, v27
	v_permlane16_swap_b32_e32 v20, v16
	v_permlane16_swap_b32_e32 v21, v17
	v_permlane16_swap_b32_e32 v22, v18
	v_permlane16_swap_b32_e32 v23, v19
	v_permlane16_swap_b32_e32 v12, v8
	v_permlane16_swap_b32_e32 v13, v9
	v_permlane16_swap_b32_e32 v14, v10
	v_permlane16_swap_b32_e32 v15, v11
	v_permlane16_swap_b32_e32 v4, v0
	v_permlane16_swap_b32_e32 v5, v1
	v_permlane16_swap_b32_e32 v6, v2
	v_permlane16_swap_b32_e32 v7, v3
	s_waitcnt vmcnt(15)
	v_lshlrev_b32_e32 v182, 16, v162
	v_and_b32_e32 v183, 0xffff0000, v162
	v_lshlrev_b32_e32 v162, 16, v163
	v_and_b32_e32 v163, 0xffff0000, v163
	v_lshlrev_b32_e32 v238, 16, v164
	v_and_b32_e32 v239, 0xffff0000, v164
	v_lshlrev_b32_e32 v164, 16, v165
	v_and_b32_e32 v165, 0xffff0000, v165
	v_pk_fma_f32 v[124:125], v[182:183], s[92:93], v[124:125] op_sel_hi:[1,0,1]
	v_pk_fma_f32 v[126:127], v[162:163], s[92:93], v[126:127] op_sel_hi:[1,0,1]
	v_pk_fma_f32 v[120:121], v[238:239], s[92:93], v[120:121] op_sel_hi:[1,0,1]
	v_pk_fma_f32 v[122:123], v[164:165], s[92:93], v[122:123] op_sel_hi:[1,0,1]
	v_cvt_pk_bf16_f32 v124, v124, v125
	v_cvt_pk_bf16_f32 v125, v126, v127
	v_cvt_pk_bf16_f32 v126, v120, v121
	v_cvt_pk_bf16_f32 v127, v122, v123
	global_store_dwordx4 v132, v[124:127], s[36:37]
	s_waitcnt vmcnt(15)
	v_lshlrev_b32_e32 v182, 16, v166
	v_and_b32_e32 v183, 0xffff0000, v166
	v_lshlrev_b32_e32 v166, 16, v167
	v_and_b32_e32 v167, 0xffff0000, v167
	v_lshlrev_b32_e32 v238, 16, v168
	v_and_b32_e32 v239, 0xffff0000, v168
	v_lshlrev_b32_e32 v168, 16, v169
	v_and_b32_e32 v169, 0xffff0000, v169
	v_pk_fma_f32 v[116:117], v[182:183], s[92:93], v[116:117] op_sel_hi:[1,0,1]
	v_pk_fma_f32 v[118:119], v[166:167], s[92:93], v[118:119] op_sel_hi:[1,0,1]
	v_pk_fma_f32 v[112:113], v[238:239], s[92:93], v[112:113] op_sel_hi:[1,0,1]
	v_pk_fma_f32 v[114:115], v[168:169], s[92:93], v[114:115] op_sel_hi:[1,0,1]
	v_cvt_pk_bf16_f32 v116, v116, v117
	v_cvt_pk_bf16_f32 v117, v118, v119
	v_cvt_pk_bf16_f32 v118, v112, v113
	v_cvt_pk_bf16_f32 v119, v114, v115
	global_store_dwordx4 v133, v[116:119], s[36:37]
	s_waitcnt vmcnt(15)
	v_lshlrev_b32_e32 v182, 16, v170
	v_and_b32_e32 v183, 0xffff0000, v170
	v_lshlrev_b32_e32 v170, 16, v171
	v_and_b32_e32 v171, 0xffff0000, v171
	v_lshlrev_b32_e32 v238, 16, v172
	v_and_b32_e32 v239, 0xffff0000, v172
	v_lshlrev_b32_e32 v172, 16, v173
	v_and_b32_e32 v173, 0xffff0000, v173
	v_pk_fma_f32 v[108:109], v[182:183], s[92:93], v[108:109] op_sel_hi:[1,0,1]
	v_pk_fma_f32 v[110:111], v[170:171], s[92:93], v[110:111] op_sel_hi:[1,0,1]
	v_pk_fma_f32 v[104:105], v[238:239], s[92:93], v[104:105] op_sel_hi:[1,0,1]
	v_pk_fma_f32 v[106:107], v[172:173], s[92:93], v[106:107] op_sel_hi:[1,0,1]
	v_cvt_pk_bf16_f32 v108, v108, v109
	v_cvt_pk_bf16_f32 v109, v110, v111
	v_cvt_pk_bf16_f32 v110, v104, v105
	v_cvt_pk_bf16_f32 v111, v106, v107
	global_store_dwordx4 v134, v[108:111], s[36:37]
	s_waitcnt vmcnt(15)
	v_lshlrev_b32_e32 v182, 16, v174
	v_and_b32_e32 v183, 0xffff0000, v174
	v_lshlrev_b32_e32 v174, 16, v175
	v_and_b32_e32 v175, 0xffff0000, v175
	v_lshlrev_b32_e32 v238, 16, v176
	v_and_b32_e32 v239, 0xffff0000, v176
	v_lshlrev_b32_e32 v176, 16, v177
	v_and_b32_e32 v177, 0xffff0000, v177
	v_pk_fma_f32 v[100:101], v[182:183], s[92:93], v[100:101] op_sel_hi:[1,0,1]
	v_pk_fma_f32 v[102:103], v[174:175], s[92:93], v[102:103] op_sel_hi:[1,0,1]
	v_pk_fma_f32 v[96:97], v[238:239], s[92:93], v[96:97] op_sel_hi:[1,0,1]
	v_pk_fma_f32 v[98:99], v[176:177], s[92:93], v[98:99] op_sel_hi:[1,0,1]
	v_cvt_pk_bf16_f32 v100, v100, v101
	v_cvt_pk_bf16_f32 v101, v102, v103
	v_cvt_pk_bf16_f32 v102, v96, v97
	v_cvt_pk_bf16_f32 v103, v98, v99
	global_store_dwordx4 v135, v[100:103], s[36:37]
	s_waitcnt vmcnt(15)
	v_lshlrev_b32_e32 v182, 16, v178
	v_and_b32_e32 v183, 0xffff0000, v178
	v_lshlrev_b32_e32 v178, 16, v179
	v_and_b32_e32 v179, 0xffff0000, v179
	v_lshlrev_b32_e32 v238, 16, v180
	v_and_b32_e32 v239, 0xffff0000, v180
	v_lshlrev_b32_e32 v180, 16, v181
	v_and_b32_e32 v181, 0xffff0000, v181
	v_pk_fma_f32 v[92:93], v[182:183], s[92:93], v[92:93] op_sel_hi:[1,0,1]
	v_pk_fma_f32 v[94:95], v[178:179], s[92:93], v[94:95] op_sel_hi:[1,0,1]
	v_pk_fma_f32 v[88:89], v[238:239], s[92:93], v[88:89] op_sel_hi:[1,0,1]
	v_pk_fma_f32 v[90:91], v[180:181], s[92:93], v[90:91] op_sel_hi:[1,0,1]
	v_cvt_pk_bf16_f32 v92, v92, v93
	v_cvt_pk_bf16_f32 v93, v94, v95
	v_cvt_pk_bf16_f32 v94, v88, v89
	v_cvt_pk_bf16_f32 v95, v90, v91
	global_store_dwordx4 v132, v[92:95], s[36:37] offset:256
	s_waitcnt vmcnt(15)
	v_lshlrev_b32_e32 v182, 16, v190
	v_and_b32_e32 v183, 0xffff0000, v190
	v_lshlrev_b32_e32 v190, 16, v191
	v_and_b32_e32 v191, 0xffff0000, v191
	v_lshlrev_b32_e32 v238, 16, v192
	v_and_b32_e32 v239, 0xffff0000, v192
	v_lshlrev_b32_e32 v192, 16, v193
	v_and_b32_e32 v193, 0xffff0000, v193
	v_pk_fma_f32 v[84:85], v[182:183], s[92:93], v[84:85] op_sel_hi:[1,0,1]
	v_pk_fma_f32 v[86:87], v[190:191], s[92:93], v[86:87] op_sel_hi:[1,0,1]
	v_pk_fma_f32 v[80:81], v[238:239], s[92:93], v[80:81] op_sel_hi:[1,0,1]
	v_pk_fma_f32 v[82:83], v[192:193], s[92:93], v[82:83] op_sel_hi:[1,0,1]
	v_cvt_pk_bf16_f32 v84, v84, v85
	v_cvt_pk_bf16_f32 v85, v86, v87
	v_cvt_pk_bf16_f32 v86, v80, v81
	v_cvt_pk_bf16_f32 v87, v82, v83
	global_store_dwordx4 v133, v[84:87], s[36:37] offset:256
	s_waitcnt vmcnt(15)
	v_lshlrev_b32_e32 v182, 16, v194
	v_and_b32_e32 v183, 0xffff0000, v194
	v_lshlrev_b32_e32 v194, 16, v195
	v_and_b32_e32 v195, 0xffff0000, v195
	v_lshlrev_b32_e32 v238, 16, v196
	v_and_b32_e32 v239, 0xffff0000, v196
	v_lshlrev_b32_e32 v196, 16, v197
	v_and_b32_e32 v197, 0xffff0000, v197
	v_pk_fma_f32 v[76:77], v[182:183], s[92:93], v[76:77] op_sel_hi:[1,0,1]
	v_pk_fma_f32 v[78:79], v[194:195], s[92:93], v[78:79] op_sel_hi:[1,0,1]
	v_pk_fma_f32 v[72:73], v[238:239], s[92:93], v[72:73] op_sel_hi:[1,0,1]
	v_pk_fma_f32 v[74:75], v[196:197], s[92:93], v[74:75] op_sel_hi:[1,0,1]
	v_cvt_pk_bf16_f32 v76, v76, v77
	v_cvt_pk_bf16_f32 v77, v78, v79
	v_cvt_pk_bf16_f32 v78, v72, v73
	v_cvt_pk_bf16_f32 v79, v74, v75
	global_store_dwordx4 v134, v[76:79], s[36:37] offset:256
	s_waitcnt vmcnt(15)
	v_lshlrev_b32_e32 v182, 16, v206
	v_and_b32_e32 v183, 0xffff0000, v206
	v_lshlrev_b32_e32 v206, 16, v207
	v_and_b32_e32 v207, 0xffff0000, v207
	v_lshlrev_b32_e32 v238, 16, v208
	v_and_b32_e32 v239, 0xffff0000, v208
	v_lshlrev_b32_e32 v208, 16, v209
	v_and_b32_e32 v209, 0xffff0000, v209
	v_pk_fma_f32 v[68:69], v[182:183], s[92:93], v[68:69] op_sel_hi:[1,0,1]
	v_pk_fma_f32 v[70:71], v[206:207], s[92:93], v[70:71] op_sel_hi:[1,0,1]
	v_pk_fma_f32 v[64:65], v[238:239], s[92:93], v[64:65] op_sel_hi:[1,0,1]
	v_pk_fma_f32 v[66:67], v[208:209], s[92:93], v[66:67] op_sel_hi:[1,0,1]
	v_cvt_pk_bf16_f32 v68, v68, v69
	v_cvt_pk_bf16_f32 v69, v70, v71
	v_cvt_pk_bf16_f32 v70, v64, v65
	v_cvt_pk_bf16_f32 v71, v66, v67
	global_store_dwordx4 v135, v[68:71], s[36:37] offset:256
	s_waitcnt vmcnt(15)
	v_lshlrev_b32_e32 v182, 16, v210
	v_and_b32_e32 v183, 0xffff0000, v210
	v_lshlrev_b32_e32 v210, 16, v211
	v_and_b32_e32 v211, 0xffff0000, v211
	v_lshlrev_b32_e32 v238, 16, v212
	v_and_b32_e32 v239, 0xffff0000, v212
	v_lshlrev_b32_e32 v212, 16, v213
	v_and_b32_e32 v213, 0xffff0000, v213
	v_pk_fma_f32 v[60:61], v[182:183], s[92:93], v[60:61] op_sel_hi:[1,0,1]
	v_pk_fma_f32 v[62:63], v[210:211], s[92:93], v[62:63] op_sel_hi:[1,0,1]
	v_pk_fma_f32 v[56:57], v[238:239], s[92:93], v[56:57] op_sel_hi:[1,0,1]
	v_pk_fma_f32 v[58:59], v[212:213], s[92:93], v[58:59] op_sel_hi:[1,0,1]
	v_cvt_pk_bf16_f32 v60, v60, v61
	v_cvt_pk_bf16_f32 v61, v62, v63
	v_cvt_pk_bf16_f32 v62, v56, v57
	v_cvt_pk_bf16_f32 v63, v58, v59
	global_store_dwordx4 v136, v[60:63], s[36:37]
	s_waitcnt vmcnt(15)
	v_lshlrev_b32_e32 v182, 16, v214
	v_and_b32_e32 v183, 0xffff0000, v214
	v_lshlrev_b32_e32 v214, 16, v215
	v_and_b32_e32 v215, 0xffff0000, v215
	v_lshlrev_b32_e32 v238, 16, v216
	v_and_b32_e32 v239, 0xffff0000, v216
	v_lshlrev_b32_e32 v216, 16, v217
	v_and_b32_e32 v217, 0xffff0000, v217
	v_pk_fma_f32 v[52:53], v[182:183], s[92:93], v[52:53] op_sel_hi:[1,0,1]
	v_pk_fma_f32 v[54:55], v[214:215], s[92:93], v[54:55] op_sel_hi:[1,0,1]
	v_pk_fma_f32 v[48:49], v[238:239], s[92:93], v[48:49] op_sel_hi:[1,0,1]
	v_pk_fma_f32 v[50:51], v[216:217], s[92:93], v[50:51] op_sel_hi:[1,0,1]
	v_cvt_pk_bf16_f32 v52, v52, v53
	v_cvt_pk_bf16_f32 v53, v54, v55
	v_cvt_pk_bf16_f32 v54, v48, v49
	v_cvt_pk_bf16_f32 v55, v50, v51
	global_store_dwordx4 v137, v[52:55], s[36:37]
	s_waitcnt vmcnt(15)
	v_lshlrev_b32_e32 v182, 16, v218
	v_and_b32_e32 v183, 0xffff0000, v218
	v_lshlrev_b32_e32 v218, 16, v219
	v_and_b32_e32 v219, 0xffff0000, v219
	v_lshlrev_b32_e32 v238, 16, v220
	v_and_b32_e32 v239, 0xffff0000, v220
	v_lshlrev_b32_e32 v220, 16, v221
	v_and_b32_e32 v221, 0xffff0000, v221
	v_pk_fma_f32 v[44:45], v[182:183], s[92:93], v[44:45] op_sel_hi:[1,0,1]
	v_pk_fma_f32 v[46:47], v[218:219], s[92:93], v[46:47] op_sel_hi:[1,0,1]
	v_pk_fma_f32 v[40:41], v[238:239], s[92:93], v[40:41] op_sel_hi:[1,0,1]
	v_pk_fma_f32 v[42:43], v[220:221], s[92:93], v[42:43] op_sel_hi:[1,0,1]
	v_cvt_pk_bf16_f32 v44, v44, v45
	v_cvt_pk_bf16_f32 v45, v46, v47
	v_cvt_pk_bf16_f32 v46, v40, v41
	v_cvt_pk_bf16_f32 v47, v42, v43
	global_store_dwordx4 v138, v[44:47], s[36:37]
	s_waitcnt vmcnt(15)
	v_lshlrev_b32_e32 v182, 16, v222
	v_and_b32_e32 v183, 0xffff0000, v222
	v_lshlrev_b32_e32 v222, 16, v223
	v_and_b32_e32 v223, 0xffff0000, v223
	v_lshlrev_b32_e32 v238, 16, v224
	v_and_b32_e32 v239, 0xffff0000, v224
	v_lshlrev_b32_e32 v224, 16, v225
	v_and_b32_e32 v225, 0xffff0000, v225
	v_pk_fma_f32 v[36:37], v[182:183], s[92:93], v[36:37] op_sel_hi:[1,0,1]
	v_pk_fma_f32 v[38:39], v[222:223], s[92:93], v[38:39] op_sel_hi:[1,0,1]
	v_pk_fma_f32 v[32:33], v[238:239], s[92:93], v[32:33] op_sel_hi:[1,0,1]
	v_pk_fma_f32 v[34:35], v[224:225], s[92:93], v[34:35] op_sel_hi:[1,0,1]
	v_cvt_pk_bf16_f32 v36, v36, v37
	v_cvt_pk_bf16_f32 v37, v38, v39
	v_cvt_pk_bf16_f32 v38, v32, v33
	v_cvt_pk_bf16_f32 v39, v34, v35
	global_store_dwordx4 v139, v[36:39], s[36:37]
	s_waitcnt vmcnt(15)
	v_lshlrev_b32_e32 v182, 16, v226
	v_and_b32_e32 v183, 0xffff0000, v226
	v_lshlrev_b32_e32 v226, 16, v227
	v_and_b32_e32 v227, 0xffff0000, v227
	v_lshlrev_b32_e32 v238, 16, v228
	v_and_b32_e32 v239, 0xffff0000, v228
	v_lshlrev_b32_e32 v228, 16, v229
	v_and_b32_e32 v229, 0xffff0000, v229
	v_pk_fma_f32 v[28:29], v[182:183], s[92:93], v[28:29] op_sel_hi:[1,0,1]
	v_pk_fma_f32 v[30:31], v[226:227], s[92:93], v[30:31] op_sel_hi:[1,0,1]
	v_pk_fma_f32 v[24:25], v[238:239], s[92:93], v[24:25] op_sel_hi:[1,0,1]
	v_pk_fma_f32 v[26:27], v[228:229], s[92:93], v[26:27] op_sel_hi:[1,0,1]
	v_cvt_pk_bf16_f32 v28, v28, v29
	v_cvt_pk_bf16_f32 v29, v30, v31
	v_cvt_pk_bf16_f32 v30, v24, v25
	v_cvt_pk_bf16_f32 v31, v26, v27
	global_store_dwordx4 v136, v[28:31], s[36:37] offset:256
	s_waitcnt vmcnt(15)
	v_lshlrev_b32_e32 v182, 16, v230
	v_and_b32_e32 v183, 0xffff0000, v230
	v_lshlrev_b32_e32 v230, 16, v231
	v_and_b32_e32 v231, 0xffff0000, v231
	v_lshlrev_b32_e32 v238, 16, v232
	v_and_b32_e32 v239, 0xffff0000, v232
	v_lshlrev_b32_e32 v232, 16, v233
	v_and_b32_e32 v233, 0xffff0000, v233
	v_pk_fma_f32 v[20:21], v[182:183], s[92:93], v[20:21] op_sel_hi:[1,0,1]
	v_pk_fma_f32 v[22:23], v[230:231], s[92:93], v[22:23] op_sel_hi:[1,0,1]
	v_pk_fma_f32 v[16:17], v[238:239], s[92:93], v[16:17] op_sel_hi:[1,0,1]
	v_pk_fma_f32 v[18:19], v[232:233], s[92:93], v[18:19] op_sel_hi:[1,0,1]
	v_cvt_pk_bf16_f32 v20, v20, v21
	v_cvt_pk_bf16_f32 v21, v22, v23
	v_cvt_pk_bf16_f32 v22, v16, v17
	v_cvt_pk_bf16_f32 v23, v18, v19
	global_store_dwordx4 v137, v[20:23], s[36:37] offset:256
	s_waitcnt vmcnt(15)
	v_lshlrev_b32_e32 v182, 16, v234
	v_and_b32_e32 v183, 0xffff0000, v234
	v_lshlrev_b32_e32 v234, 16, v235
	v_and_b32_e32 v235, 0xffff0000, v235
	v_lshlrev_b32_e32 v238, 16, v236
	v_and_b32_e32 v239, 0xffff0000, v236
	v_lshlrev_b32_e32 v236, 16, v237
	v_and_b32_e32 v237, 0xffff0000, v237
	v_pk_fma_f32 v[12:13], v[182:183], s[92:93], v[12:13] op_sel_hi:[1,0,1]
	v_pk_fma_f32 v[14:15], v[234:235], s[92:93], v[14:15] op_sel_hi:[1,0,1]
	v_pk_fma_f32 v[8:9], v[238:239], s[92:93], v[8:9] op_sel_hi:[1,0,1]
	v_pk_fma_f32 v[10:11], v[236:237], s[92:93], v[10:11] op_sel_hi:[1,0,1]
	v_cvt_pk_bf16_f32 v12, v12, v13
	v_cvt_pk_bf16_f32 v13, v14, v15
	v_cvt_pk_bf16_f32 v14, v8, v9
	v_cvt_pk_bf16_f32 v15, v10, v11
	global_store_dwordx4 v138, v[12:15], s[36:37] offset:256
	s_waitcnt vmcnt(15)
	v_lshlrev_b32_e32 v182, 16, v240
	v_and_b32_e32 v183, 0xffff0000, v240
	v_lshlrev_b32_e32 v240, 16, v241
	v_and_b32_e32 v241, 0xffff0000, v241
	v_lshlrev_b32_e32 v238, 16, v242
	v_and_b32_e32 v239, 0xffff0000, v242
	v_lshlrev_b32_e32 v242, 16, v243
	v_and_b32_e32 v243, 0xffff0000, v243
	v_pk_fma_f32 v[4:5], v[182:183], s[92:93], v[4:5] op_sel_hi:[1,0,1]
	v_pk_fma_f32 v[6:7], v[240:241], s[92:93], v[6:7] op_sel_hi:[1,0,1]
	v_pk_fma_f32 v[0:1], v[238:239], s[92:93], v[0:1] op_sel_hi:[1,0,1]
	v_pk_fma_f32 v[2:3], v[242:243], s[92:93], v[2:3] op_sel_hi:[1,0,1]
	v_cvt_pk_bf16_f32 v4, v4, v5
	v_cvt_pk_bf16_f32 v5, v6, v7
	v_cvt_pk_bf16_f32 v6, v0, v1
	v_cvt_pk_bf16_f32 v7, v2, v3
	global_store_dwordx4 v139, v[4:7], s[36:37] offset:256
	s_andn2_b64 vcc, exec, s[8:9]
	s_waitcnt vmcnt(22)
	s_cbranch_vccz .LBB0_435
	s_branch .Lseam_res_l1

.LBB0_439:
	s_lshr_b32 s3, s3, 21
	s_add_i32 s3, s2, s3
	s_ashr_i32 s14, s3, 11
	s_and_b32 s3, s3, 0xf800
	s_lshr_b32 s1, s1, 19
	s_sub_i32 s2, s2, s3
	s_add_i32 s1, s0, s1
	s_sext_i32_i16 s2, s2
	s_ashr_i32 s13, s1, 13
	s_and_b32 s1, s1, 0xffffe000
	s_ashr_i32 s11, s2, 7
	s_sub_i32 s0, s0, s1
	s_ashr_i32 s15, s14, 31
	s_lshl_b32 s1, s13, 4
	s_lshl_b64 s[2:3], s[14:15], 27
	s_add_i32 s14, s1, s11
	s_ashr_i32 s1, s0, 31
	s_ashr_i32 s15, s14, 31
	v_lshl_add_u64 v[156:157], v[128:129], 0, s[0:1]
	v_lshl_add_u64 v[158:159], v[130:131], 0, s[2:3]
	s_lshl_b64 s[0:1], s[14:15], 21
	v_lshlrev_b64 v[156:157], 8, v[156:157]
	v_lshl_add_u64 v[158:159], v[158:159], 0, s[0:1]
	v_lshl_add_u64 v[160:161], v[158:159], 0, v[156:157]
	v_bfe_u32 v178, v187, 4, 1
	v_mov_b32_e32 v179, 0
	v_mul_u32_u24_e32 v178, 24, v178
	s_mov_b64 s[0:1], 0x1000
	s_mov_b64 s[2:3], 0x2000
	v_lshl_add_u64 v[160:161], v[160:161], 0, v[178:179]
	v_lshl_add_u64 v[162:163], v[160:161], 0, s[0:1]
	v_lshl_add_u64 v[164:165], v[162:163], 0, s[2:3]
	s_mov_b64 s[2:3], 0x200000
	v_lshl_add_u64 v[166:167], v[162:163], 0, s[2:3]
	v_lshl_add_u64 v[168:169], v[164:165], 0, s[2:3]
	s_mov_b64 s[2:3], 0x8000
	v_lshl_add_u64 v[170:171], v[162:163], 0, s[2:3]
	v_lshl_add_u64 v[172:173], v[164:165], 0, s[2:3]
	v_lshl_add_u64 v[174:175], v[166:167], 0, s[2:3]
	v_lshl_add_u64 v[176:177], v[168:169], 0, s[2:3]
	v_cvt_pk_bf16_f32 v124, v124, v125
	v_cvt_pk_bf16_f32 v125, v126, v127
	v_cvt_pk_bf16_f32 v126, v120, v121
	v_cvt_pk_bf16_f32 v127, v122, v123
	v_cvt_pk_bf16_f32 v116, v116, v117
	v_cvt_pk_bf16_f32 v117, v118, v119
	v_cvt_pk_bf16_f32 v118, v112, v113
	v_cvt_pk_bf16_f32 v119, v114, v115
	v_permlane16_swap_b32_e32 v124, v126
	v_permlane16_swap_b32_e32 v125, v127
	global_store_dwordx4 v[162:163], v[124:127], off offset:-4096
	v_cvt_pk_bf16_f32 v108, v108, v109
	v_cvt_pk_bf16_f32 v109, v110, v111
	v_cvt_pk_bf16_f32 v110, v104, v105
	v_cvt_pk_bf16_f32 v111, v106, v107
	v_permlane16_swap_b32_e32 v116, v118
	v_permlane16_swap_b32_e32 v117, v119
	global_store_dwordx4 v[162:163], v[116:119], off
	v_cvt_pk_bf16_f32 v100, v100, v101
	v_cvt_pk_bf16_f32 v101, v102, v103
	v_cvt_pk_bf16_f32 v102, v96, v97
	v_cvt_pk_bf16_f32 v103, v98, v99
	v_permlane16_swap_b32_e32 v108, v110
	v_permlane16_swap_b32_e32 v109, v111
	global_store_dwordx4 v[164:165], v[108:111], off offset:-4096
	v_cvt_pk_bf16_f32 v92, v92, v93
	v_cvt_pk_bf16_f32 v93, v94, v95
	v_cvt_pk_bf16_f32 v94, v88, v89
	v_cvt_pk_bf16_f32 v95, v90, v91
	v_permlane16_swap_b32_e32 v100, v102
	v_permlane16_swap_b32_e32 v101, v103
	global_store_dwordx4 v[164:165], v[100:103], off
	v_cvt_pk_bf16_f32 v84, v84, v85
	v_cvt_pk_bf16_f32 v85, v86, v87
	v_cvt_pk_bf16_f32 v86, v80, v81
	v_cvt_pk_bf16_f32 v87, v82, v83
	v_permlane16_swap_b32_e32 v92, v94
	v_permlane16_swap_b32_e32 v93, v95
	global_store_dwordx4 v[166:167], v[92:95], off offset:-4096
	v_cvt_pk_bf16_f32 v76, v76, v77
	v_cvt_pk_bf16_f32 v77, v78, v79
	v_cvt_pk_bf16_f32 v78, v72, v73
	v_cvt_pk_bf16_f32 v79, v74, v75
	v_permlane16_swap_b32_e32 v84, v86
	v_permlane16_swap_b32_e32 v85, v87
	global_store_dwordx4 v[166:167], v[84:87], off
	v_cvt_pk_bf16_f32 v68, v68, v69
	v_cvt_pk_bf16_f32 v69, v70, v71
	v_cvt_pk_bf16_f32 v70, v64, v65
	v_cvt_pk_bf16_f32 v71, v66, v67
	v_permlane16_swap_b32_e32 v76, v78
	v_permlane16_swap_b32_e32 v77, v79
	global_store_dwordx4 v[168:169], v[76:79], off offset:-4096
	v_cvt_pk_bf16_f32 v60, v60, v61
	v_cvt_pk_bf16_f32 v61, v62, v63
	v_cvt_pk_bf16_f32 v62, v56, v57
	v_cvt_pk_bf16_f32 v63, v58, v59
	v_permlane16_swap_b32_e32 v68, v70
	v_permlane16_swap_b32_e32 v69, v71
	global_store_dwordx4 v[168:169], v[68:71], off
	v_cvt_pk_bf16_f32 v52, v52, v53
	v_cvt_pk_bf16_f32 v53, v54, v55
	v_cvt_pk_bf16_f32 v54, v48, v49
	v_cvt_pk_bf16_f32 v55, v50, v51
	v_permlane16_swap_b32_e32 v60, v62
	v_permlane16_swap_b32_e32 v61, v63
	global_store_dwordx4 v[170:171], v[60:63], off offset:-4096
	v_cvt_pk_bf16_f32 v44, v44, v45
	v_cvt_pk_bf16_f32 v45, v46, v47
	v_cvt_pk_bf16_f32 v46, v40, v41
	v_cvt_pk_bf16_f32 v47, v42, v43
	v_permlane16_swap_b32_e32 v52, v54
	v_permlane16_swap_b32_e32 v53, v55
	global_store_dwordx4 v[170:171], v[52:55], off
	v_cvt_pk_bf16_f32 v36, v36, v37
	v_cvt_pk_bf16_f32 v37, v38, v39
	v_cvt_pk_bf16_f32 v38, v32, v33
	v_cvt_pk_bf16_f32 v39, v34, v35
	v_permlane16_swap_b32_e32 v44, v46
	v_permlane16_swap_b32_e32 v45, v47
	global_store_dwordx4 v[172:173], v[44:47], off offset:-4096
	v_cvt_pk_bf16_f32 v28, v28, v29
	v_cvt_pk_bf16_f32 v29, v30, v31
	v_cvt_pk_bf16_f32 v30, v24, v25
	v_cvt_pk_bf16_f32 v31, v26, v27
	v_permlane16_swap_b32_e32 v36, v38
	v_permlane16_swap_b32_e32 v37, v39
	global_store_dwordx4 v[172:173], v[36:39], off
	v_cvt_pk_bf16_f32 v20, v20, v21
	v_cvt_pk_bf16_f32 v21, v22, v23
	v_cvt_pk_bf16_f32 v22, v16, v17
	v_cvt_pk_bf16_f32 v23, v18, v19
	v_permlane16_swap_b32_e32 v28, v30
	v_permlane16_swap_b32_e32 v29, v31
	global_store_dwordx4 v[174:175], v[28:31], off offset:-4096
	v_cvt_pk_bf16_f32 v12, v12, v13
	v_cvt_pk_bf16_f32 v13, v14, v15
	v_cvt_pk_bf16_f32 v14, v8, v9
	v_cvt_pk_bf16_f32 v15, v10, v11
	v_permlane16_swap_b32_e32 v20, v22
	v_permlane16_swap_b32_e32 v21, v23
	global_store_dwordx4 v[174:175], v[20:23], off
	v_cvt_pk_bf16_f32 v4, v4, v5
	v_cvt_pk_bf16_f32 v5, v6, v7
	v_cvt_pk_bf16_f32 v6, v0, v1
	v_cvt_pk_bf16_f32 v7, v2, v3
	v_permlane16_swap_b32_e32 v12, v14
	v_permlane16_swap_b32_e32 v13, v15
	global_store_dwordx4 v[176:177], v[12:15], off offset:-4096
	s_nop 1
	v_permlane16_swap_b32_e32 v4, v6
	v_permlane16_swap_b32_e32 v5, v7
	global_store_dwordx4 v[176:177], v[4:7], off
	s_mov_b32 s2, s10
	s_mov_b32 s0, s12
	s_movk_i32 s1, 0x3000
	s_mov_b32 s3, 0
	s_andn2_b64 vcc, exec, s[8:9]
	s_waitcnt vmcnt(38)
	s_cbranch_vccz .LBB0_448
	s_branch .Lseam_qkv0

.LBB0_674:
	v_add_u32_e32 v182, s10, v153
	v_or_b32_e32 v183, s12, v128
	s_mov_b32 s10, s8
	v_bfe_u32 v238, v187, 4, 1
	v_lshl_add_u32 v182, v182, 11, v183
	v_mul_u32_u24_e32 v238, 24, v238
	v_lshl_add_u32 v132, v182, 1, v238
	v_add_u32_e32 v133, 0x10000, v132
	v_add_u32_e32 v134, 0x20000, v132
	v_add_u32_e32 v135, 0x30000, v132
	v_add_u32_e32 v136, 0x80000, v132
	v_add_u32_e32 v137, 0x90000, v132
	v_add_u32_e32 v138, 0xa0000, v132
	v_add_u32_e32 v139, 0xb0000, v132
	global_load_dwordx4 v[162:165], v132, s[34:35]
	global_load_dwordx4 v[166:169], v133, s[34:35]
	global_load_dwordx4 v[170:173], v134, s[34:35]
	global_load_dwordx4 v[174:177], v135, s[34:35]
	global_load_dwordx4 v[178:181], v132, s[34:35] offset:256
	global_load_dwordx4 v[190:193], v133, s[34:35] offset:256
	global_load_dwordx4 v[194:197], v134, s[34:35] offset:256
	global_load_dwordx4 v[206:209], v135, s[34:35] offset:256
	global_load_dwordx4 v[210:213], v136, s[34:35]
	global_load_dwordx4 v[214:217], v137, s[34:35]
	global_load_dwordx4 v[218:221], v138, s[34:35]
	global_load_dwordx4 v[222:225], v139, s[34:35]
	global_load_dwordx4 v[226:229], v136, s[34:35] offset:256
	global_load_dwordx4 v[230:233], v137, s[34:35] offset:256
	global_load_dwordx4 v[234:237], v138, s[34:35] offset:256
	global_load_dwordx4 v[240:243], v139, s[34:35] offset:256
	v_permlane16_swap_b32_e32 v124, v120
	v_permlane16_swap_b32_e32 v125, v121
	v_permlane16_swap_b32_e32 v126, v122
	v_permlane16_swap_b32_e32 v127, v123
	v_permlane16_swap_b32_e32 v116, v112
	v_permlane16_swap_b32_e32 v117, v113
	v_permlane16_swap_b32_e32 v118, v114
	v_permlane16_swap_b32_e32 v119, v115
	v_permlane16_swap_b32_e32 v108, v104
	v_permlane16_swap_b32_e32 v109, v105
	v_permlane16_swap_b32_e32 v110, v106
	v_permlane16_swap_b32_e32 v111, v107
	v_permlane16_swap_b32_e32 v100, v96
	v_permlane16_swap_b32_e32 v101, v97
	v_permlane16_swap_b32_e32 v102, v98
	v_permlane16_swap_b32_e32 v103, v99
	v_permlane16_swap_b32_e32 v92, v88
	v_permlane16_swap_b32_e32 v93, v89
	v_permlane16_swap_b32_e32 v94, v90
	v_permlane16_swap_b32_e32 v95, v91
	v_permlane16_swap_b32_e32 v84, v80
	v_permlane16_swap_b32_e32 v85, v81
	v_permlane16_swap_b32_e32 v86, v82
	v_permlane16_swap_b32_e32 v87, v83
	v_permlane16_swap_b32_e32 v76, v72
	v_permlane16_swap_b32_e32 v77, v73
	v_permlane16_swap_b32_e32 v78, v74
	v_permlane16_swap_b32_e32 v79, v75
	v_permlane16_swap_b32_e32 v68, v64
	v_permlane16_swap_b32_e32 v69, v65
	v_permlane16_swap_b32_e32 v70, v66
	v_permlane16_swap_b32_e32 v71, v67
	v_permlane16_swap_b32_e32 v60, v56
	v_permlane16_swap_b32_e32 v61, v57
	v_permlane16_swap_b32_e32 v62, v58
	v_permlane16_swap_b32_e32 v63, v59
	v_permlane16_swap_b32_e32 v52, v48
	v_permlane16_swap_b32_e32 v53, v49
	v_permlane16_swap_b32_e32 v54, v50
	v_permlane16_swap_b32_e32 v55, v51
	v_permlane16_swap_b32_e32 v44, v40
	v_permlane16_swap_b32_e32 v45, v41
	v_permlane16_swap_b32_e32 v46, v42
	v_permlane16_swap_b32_e32 v47, v43
	v_permlane16_swap_b32_e32 v36, v32
	v_permlane16_swap_b32_e32 v37, v33
	v_permlane16_swap_b32_e32 v38, v34
	v_permlane16_swap_b32_e32 v39, v35
	v_permlane16_swap_b32_e32 v28, v24
	v_permlane16_swap_b32_e32 v29, v25
	v_permlane16_swap_b32_e32 v30, v26
	v_permlane16_swap_b32_e32 v31, v27
	v_permlane16_swap_b32_e32 v20, v16
	v_permlane16_swap_b32_e32 v21, v17
	v_permlane16_swap_b32_e32 v22, v18
	v_permlane16_swap_b32_e32 v23, v19
	v_permlane16_swap_b32_e32 v12, v8
	v_permlane16_swap_b32_e32 v13, v9
	v_permlane16_swap_b32_e32 v14, v10
	v_permlane16_swap_b32_e32 v15, v11
	v_permlane16_swap_b32_e32 v4, v0
	v_permlane16_swap_b32_e32 v5, v1
	v_permlane16_swap_b32_e32 v6, v2
	v_permlane16_swap_b32_e32 v7, v3
	s_waitcnt vmcnt(15)
	v_lshlrev_b32_e32 v182, 16, v162
	v_and_b32_e32 v183, 0xffff0000, v162
	v_lshlrev_b32_e32 v162, 16, v163
	v_and_b32_e32 v163, 0xffff0000, v163
	v_lshlrev_b32_e32 v238, 16, v164
	v_and_b32_e32 v239, 0xffff0000, v164
	v_lshlrev_b32_e32 v164, 16, v165
	v_and_b32_e32 v165, 0xffff0000, v165
	v_pk_fma_f32 v[124:125], v[182:183], s[92:93], v[124:125] op_sel_hi:[1,0,1]
	v_pk_fma_f32 v[126:127], v[162:163], s[92:93], v[126:127] op_sel_hi:[1,0,1]
	v_pk_fma_f32 v[120:121], v[238:239], s[92:93], v[120:121] op_sel_hi:[1,0,1]
	v_pk_fma_f32 v[122:123], v[164:165], s[92:93], v[122:123] op_sel_hi:[1,0,1]
	v_cvt_pk_bf16_f32 v124, v124, v125
	v_cvt_pk_bf16_f32 v125, v126, v127
	v_cvt_pk_bf16_f32 v126, v120, v121
	v_cvt_pk_bf16_f32 v127, v122, v123
	global_store_dwordx4 v132, v[124:127], s[36:37]
	s_waitcnt vmcnt(15)
	v_lshlrev_b32_e32 v182, 16, v166
	v_and_b32_e32 v183, 0xffff0000, v166
	v_lshlrev_b32_e32 v166, 16, v167
	v_and_b32_e32 v167, 0xffff0000, v167
	v_lshlrev_b32_e32 v238, 16, v168
	v_and_b32_e32 v239, 0xffff0000, v168
	v_lshlrev_b32_e32 v168, 16, v169
	v_and_b32_e32 v169, 0xffff0000, v169
	v_pk_fma_f32 v[116:117], v[182:183], s[92:93], v[116:117] op_sel_hi:[1,0,1]
	v_pk_fma_f32 v[118:119], v[166:167], s[92:93], v[118:119] op_sel_hi:[1,0,1]
	v_pk_fma_f32 v[112:113], v[238:239], s[92:93], v[112:113] op_sel_hi:[1,0,1]
	v_pk_fma_f32 v[114:115], v[168:169], s[92:93], v[114:115] op_sel_hi:[1,0,1]
	v_cvt_pk_bf16_f32 v116, v116, v117
	v_cvt_pk_bf16_f32 v117, v118, v119
	v_cvt_pk_bf16_f32 v118, v112, v113
	v_cvt_pk_bf16_f32 v119, v114, v115
	global_store_dwordx4 v133, v[116:119], s[36:37]
	s_waitcnt vmcnt(15)
	v_lshlrev_b32_e32 v182, 16, v170
	v_and_b32_e32 v183, 0xffff0000, v170
	v_lshlrev_b32_e32 v170, 16, v171
	v_and_b32_e32 v171, 0xffff0000, v171
	v_lshlrev_b32_e32 v238, 16, v172
	v_and_b32_e32 v239, 0xffff0000, v172
	v_lshlrev_b32_e32 v172, 16, v173
	v_and_b32_e32 v173, 0xffff0000, v173
	v_pk_fma_f32 v[108:109], v[182:183], s[92:93], v[108:109] op_sel_hi:[1,0,1]
	v_pk_fma_f32 v[110:111], v[170:171], s[92:93], v[110:111] op_sel_hi:[1,0,1]
	v_pk_fma_f32 v[104:105], v[238:239], s[92:93], v[104:105] op_sel_hi:[1,0,1]
	v_pk_fma_f32 v[106:107], v[172:173], s[92:93], v[106:107] op_sel_hi:[1,0,1]
	v_cvt_pk_bf16_f32 v108, v108, v109
	v_cvt_pk_bf16_f32 v109, v110, v111
	v_cvt_pk_bf16_f32 v110, v104, v105
	v_cvt_pk_bf16_f32 v111, v106, v107
	global_store_dwordx4 v134, v[108:111], s[36:37]
	s_waitcnt vmcnt(15)
	v_lshlrev_b32_e32 v182, 16, v174
	v_and_b32_e32 v183, 0xffff0000, v174
	v_lshlrev_b32_e32 v174, 16, v175
	v_and_b32_e32 v175, 0xffff0000, v175
	v_lshlrev_b32_e32 v238, 16, v176
	v_and_b32_e32 v239, 0xffff0000, v176
	v_lshlrev_b32_e32 v176, 16, v177
	v_and_b32_e32 v177, 0xffff0000, v177
	v_pk_fma_f32 v[100:101], v[182:183], s[92:93], v[100:101] op_sel_hi:[1,0,1]
	v_pk_fma_f32 v[102:103], v[174:175], s[92:93], v[102:103] op_sel_hi:[1,0,1]
	v_pk_fma_f32 v[96:97], v[238:239], s[92:93], v[96:97] op_sel_hi:[1,0,1]
	v_pk_fma_f32 v[98:99], v[176:177], s[92:93], v[98:99] op_sel_hi:[1,0,1]
	v_cvt_pk_bf16_f32 v100, v100, v101
	v_cvt_pk_bf16_f32 v101, v102, v103
	v_cvt_pk_bf16_f32 v102, v96, v97
	v_cvt_pk_bf16_f32 v103, v98, v99
	global_store_dwordx4 v135, v[100:103], s[36:37]
	s_waitcnt vmcnt(15)
	v_lshlrev_b32_e32 v182, 16, v178
	v_and_b32_e32 v183, 0xffff0000, v178
	v_lshlrev_b32_e32 v178, 16, v179
	v_and_b32_e32 v179, 0xffff0000, v179
	v_lshlrev_b32_e32 v238, 16, v180
	v_and_b32_e32 v239, 0xffff0000, v180
	v_lshlrev_b32_e32 v180, 16, v181
	v_and_b32_e32 v181, 0xffff0000, v181
	v_pk_fma_f32 v[92:93], v[182:183], s[92:93], v[92:93] op_sel_hi:[1,0,1]
	v_pk_fma_f32 v[94:95], v[178:179], s[92:93], v[94:95] op_sel_hi:[1,0,1]
	v_pk_fma_f32 v[88:89], v[238:239], s[92:93], v[88:89] op_sel_hi:[1,0,1]
	v_pk_fma_f32 v[90:91], v[180:181], s[92:93], v[90:91] op_sel_hi:[1,0,1]
	v_cvt_pk_bf16_f32 v92, v92, v93
	v_cvt_pk_bf16_f32 v93, v94, v95
	v_cvt_pk_bf16_f32 v94, v88, v89
	v_cvt_pk_bf16_f32 v95, v90, v91
	global_store_dwordx4 v132, v[92:95], s[36:37] offset:256
	s_waitcnt vmcnt(15)
	v_lshlrev_b32_e32 v182, 16, v190
	v_and_b32_e32 v183, 0xffff0000, v190
	v_lshlrev_b32_e32 v190, 16, v191
	v_and_b32_e32 v191, 0xffff0000, v191
	v_lshlrev_b32_e32 v238, 16, v192
	v_and_b32_e32 v239, 0xffff0000, v192
	v_lshlrev_b32_e32 v192, 16, v193
	v_and_b32_e32 v193, 0xffff0000, v193
	v_pk_fma_f32 v[84:85], v[182:183], s[92:93], v[84:85] op_sel_hi:[1,0,1]
	v_pk_fma_f32 v[86:87], v[190:191], s[92:93], v[86:87] op_sel_hi:[1,0,1]
	v_pk_fma_f32 v[80:81], v[238:239], s[92:93], v[80:81] op_sel_hi:[1,0,1]
	v_pk_fma_f32 v[82:83], v[192:193], s[92:93], v[82:83] op_sel_hi:[1,0,1]
	v_cvt_pk_bf16_f32 v84, v84, v85
	v_cvt_pk_bf16_f32 v85, v86, v87
	v_cvt_pk_bf16_f32 v86, v80, v81
	v_cvt_pk_bf16_f32 v87, v82, v83
	global_store_dwordx4 v133, v[84:87], s[36:37] offset:256
	s_waitcnt vmcnt(15)
	v_lshlrev_b32_e32 v182, 16, v194
	v_and_b32_e32 v183, 0xffff0000, v194
	v_lshlrev_b32_e32 v194, 16, v195
	v_and_b32_e32 v195, 0xffff0000, v195
	v_lshlrev_b32_e32 v238, 16, v196
	v_and_b32_e32 v239, 0xffff0000, v196
	v_lshlrev_b32_e32 v196, 16, v197
	v_and_b32_e32 v197, 0xffff0000, v197
	v_pk_fma_f32 v[76:77], v[182:183], s[92:93], v[76:77] op_sel_hi:[1,0,1]
	v_pk_fma_f32 v[78:79], v[194:195], s[92:93], v[78:79] op_sel_hi:[1,0,1]
	v_pk_fma_f32 v[72:73], v[238:239], s[92:93], v[72:73] op_sel_hi:[1,0,1]
	v_pk_fma_f32 v[74:75], v[196:197], s[92:93], v[74:75] op_sel_hi:[1,0,1]
	v_cvt_pk_bf16_f32 v76, v76, v77
	v_cvt_pk_bf16_f32 v77, v78, v79
	v_cvt_pk_bf16_f32 v78, v72, v73
	v_cvt_pk_bf16_f32 v79, v74, v75
	global_store_dwordx4 v134, v[76:79], s[36:37] offset:256
	s_waitcnt vmcnt(15)
	v_lshlrev_b32_e32 v182, 16, v206
	v_and_b32_e32 v183, 0xffff0000, v206
	v_lshlrev_b32_e32 v206, 16, v207
	v_and_b32_e32 v207, 0xffff0000, v207
	v_lshlrev_b32_e32 v238, 16, v208
	v_and_b32_e32 v239, 0xffff0000, v208
	v_lshlrev_b32_e32 v208, 16, v209
	v_and_b32_e32 v209, 0xffff0000, v209
	v_pk_fma_f32 v[68:69], v[182:183], s[92:93], v[68:69] op_sel_hi:[1,0,1]
	v_pk_fma_f32 v[70:71], v[206:207], s[92:93], v[70:71] op_sel_hi:[1,0,1]
	v_pk_fma_f32 v[64:65], v[238:239], s[92:93], v[64:65] op_sel_hi:[1,0,1]
	v_pk_fma_f32 v[66:67], v[208:209], s[92:93], v[66:67] op_sel_hi:[1,0,1]
	v_cvt_pk_bf16_f32 v68, v68, v69
	v_cvt_pk_bf16_f32 v69, v70, v71
	v_cvt_pk_bf16_f32 v70, v64, v65
	v_cvt_pk_bf16_f32 v71, v66, v67
	global_store_dwordx4 v135, v[68:71], s[36:37] offset:256
	s_waitcnt vmcnt(15)
	v_lshlrev_b32_e32 v182, 16, v210
	v_and_b32_e32 v183, 0xffff0000, v210
	v_lshlrev_b32_e32 v210, 16, v211
	v_and_b32_e32 v211, 0xffff0000, v211
	v_lshlrev_b32_e32 v238, 16, v212
	v_and_b32_e32 v239, 0xffff0000, v212
	v_lshlrev_b32_e32 v212, 16, v213
	v_and_b32_e32 v213, 0xffff0000, v213
	v_pk_fma_f32 v[60:61], v[182:183], s[92:93], v[60:61] op_sel_hi:[1,0,1]
	v_pk_fma_f32 v[62:63], v[210:211], s[92:93], v[62:63] op_sel_hi:[1,0,1]
	v_pk_fma_f32 v[56:57], v[238:239], s[92:93], v[56:57] op_sel_hi:[1,0,1]
	v_pk_fma_f32 v[58:59], v[212:213], s[92:93], v[58:59] op_sel_hi:[1,0,1]
	v_cvt_pk_bf16_f32 v60, v60, v61
	v_cvt_pk_bf16_f32 v61, v62, v63
	v_cvt_pk_bf16_f32 v62, v56, v57
	v_cvt_pk_bf16_f32 v63, v58, v59
	global_store_dwordx4 v136, v[60:63], s[36:37]
	s_waitcnt vmcnt(15)
	v_lshlrev_b32_e32 v182, 16, v214
	v_and_b32_e32 v183, 0xffff0000, v214
	v_lshlrev_b32_e32 v214, 16, v215
	v_and_b32_e32 v215, 0xffff0000, v215
	v_lshlrev_b32_e32 v238, 16, v216
	v_and_b32_e32 v239, 0xffff0000, v216
	v_lshlrev_b32_e32 v216, 16, v217
	v_and_b32_e32 v217, 0xffff0000, v217
	v_pk_fma_f32 v[52:53], v[182:183], s[92:93], v[52:53] op_sel_hi:[1,0,1]
	v_pk_fma_f32 v[54:55], v[214:215], s[92:93], v[54:55] op_sel_hi:[1,0,1]
	v_pk_fma_f32 v[48:49], v[238:239], s[92:93], v[48:49] op_sel_hi:[1,0,1]
	v_pk_fma_f32 v[50:51], v[216:217], s[92:93], v[50:51] op_sel_hi:[1,0,1]
	v_cvt_pk_bf16_f32 v52, v52, v53
	v_cvt_pk_bf16_f32 v53, v54, v55
	v_cvt_pk_bf16_f32 v54, v48, v49
	v_cvt_pk_bf16_f32 v55, v50, v51
	global_store_dwordx4 v137, v[52:55], s[36:37]
	s_waitcnt vmcnt(15)
	v_lshlrev_b32_e32 v182, 16, v218
	v_and_b32_e32 v183, 0xffff0000, v218
	v_lshlrev_b32_e32 v218, 16, v219
	v_and_b32_e32 v219, 0xffff0000, v219
	v_lshlrev_b32_e32 v238, 16, v220
	v_and_b32_e32 v239, 0xffff0000, v220
	v_lshlrev_b32_e32 v220, 16, v221
	v_and_b32_e32 v221, 0xffff0000, v221
	v_pk_fma_f32 v[44:45], v[182:183], s[92:93], v[44:45] op_sel_hi:[1,0,1]
	v_pk_fma_f32 v[46:47], v[218:219], s[92:93], v[46:47] op_sel_hi:[1,0,1]
	v_pk_fma_f32 v[40:41], v[238:239], s[92:93], v[40:41] op_sel_hi:[1,0,1]
	v_pk_fma_f32 v[42:43], v[220:221], s[92:93], v[42:43] op_sel_hi:[1,0,1]
	v_cvt_pk_bf16_f32 v44, v44, v45
	v_cvt_pk_bf16_f32 v45, v46, v47
	v_cvt_pk_bf16_f32 v46, v40, v41
	v_cvt_pk_bf16_f32 v47, v42, v43
	global_store_dwordx4 v138, v[44:47], s[36:37]
	s_waitcnt vmcnt(15)
	v_lshlrev_b32_e32 v182, 16, v222
	v_and_b32_e32 v183, 0xffff0000, v222
	v_lshlrev_b32_e32 v222, 16, v223
	v_and_b32_e32 v223, 0xffff0000, v223
	v_lshlrev_b32_e32 v238, 16, v224
	v_and_b32_e32 v239, 0xffff0000, v224
	v_lshlrev_b32_e32 v224, 16, v225
	v_and_b32_e32 v225, 0xffff0000, v225
	v_pk_fma_f32 v[36:37], v[182:183], s[92:93], v[36:37] op_sel_hi:[1,0,1]
	v_pk_fma_f32 v[38:39], v[222:223], s[92:93], v[38:39] op_sel_hi:[1,0,1]
	v_pk_fma_f32 v[32:33], v[238:239], s[92:93], v[32:33] op_sel_hi:[1,0,1]
	v_pk_fma_f32 v[34:35], v[224:225], s[92:93], v[34:35] op_sel_hi:[1,0,1]
	v_cvt_pk_bf16_f32 v36, v36, v37
	v_cvt_pk_bf16_f32 v37, v38, v39
	v_cvt_pk_bf16_f32 v38, v32, v33
	v_cvt_pk_bf16_f32 v39, v34, v35
	global_store_dwordx4 v139, v[36:39], s[36:37]
	s_waitcnt vmcnt(15)
	v_lshlrev_b32_e32 v182, 16, v226
	v_and_b32_e32 v183, 0xffff0000, v226
	v_lshlrev_b32_e32 v226, 16, v227
	v_and_b32_e32 v227, 0xffff0000, v227
	v_lshlrev_b32_e32 v238, 16, v228
	v_and_b32_e32 v239, 0xffff0000, v228
	v_lshlrev_b32_e32 v228, 16, v229
	v_and_b32_e32 v229, 0xffff0000, v229
	v_pk_fma_f32 v[28:29], v[182:183], s[92:93], v[28:29] op_sel_hi:[1,0,1]
	v_pk_fma_f32 v[30:31], v[226:227], s[92:93], v[30:31] op_sel_hi:[1,0,1]
	v_pk_fma_f32 v[24:25], v[238:239], s[92:93], v[24:25] op_sel_hi:[1,0,1]
	v_pk_fma_f32 v[26:27], v[228:229], s[92:93], v[26:27] op_sel_hi:[1,0,1]
	v_cvt_pk_bf16_f32 v28, v28, v29
	v_cvt_pk_bf16_f32 v29, v30, v31
	v_cvt_pk_bf16_f32 v30, v24, v25
	v_cvt_pk_bf16_f32 v31, v26, v27
	global_store_dwordx4 v136, v[28:31], s[36:37] offset:256
	s_waitcnt vmcnt(15)
	v_lshlrev_b32_e32 v182, 16, v230
	v_and_b32_e32 v183, 0xffff0000, v230
	v_lshlrev_b32_e32 v230, 16, v231
	v_and_b32_e32 v231, 0xffff0000, v231
	v_lshlrev_b32_e32 v238, 16, v232
	v_and_b32_e32 v239, 0xffff0000, v232
	v_lshlrev_b32_e32 v232, 16, v233
	v_and_b32_e32 v233, 0xffff0000, v233
	v_pk_fma_f32 v[20:21], v[182:183], s[92:93], v[20:21] op_sel_hi:[1,0,1]
	v_pk_fma_f32 v[22:23], v[230:231], s[92:93], v[22:23] op_sel_hi:[1,0,1]
	v_pk_fma_f32 v[16:17], v[238:239], s[92:93], v[16:17] op_sel_hi:[1,0,1]
	v_pk_fma_f32 v[18:19], v[232:233], s[92:93], v[18:19] op_sel_hi:[1,0,1]
	v_cvt_pk_bf16_f32 v20, v20, v21
	v_cvt_pk_bf16_f32 v21, v22, v23
	v_cvt_pk_bf16_f32 v22, v16, v17
	v_cvt_pk_bf16_f32 v23, v18, v19
	global_store_dwordx4 v137, v[20:23], s[36:37] offset:256
	s_waitcnt vmcnt(15)
	v_lshlrev_b32_e32 v182, 16, v234
	v_and_b32_e32 v183, 0xffff0000, v234
	v_lshlrev_b32_e32 v234, 16, v235
	v_and_b32_e32 v235, 0xffff0000, v235
	v_lshlrev_b32_e32 v238, 16, v236
	v_and_b32_e32 v239, 0xffff0000, v236
	v_lshlrev_b32_e32 v236, 16, v237
	v_and_b32_e32 v237, 0xffff0000, v237
	v_pk_fma_f32 v[12:13], v[182:183], s[92:93], v[12:13] op_sel_hi:[1,0,1]
	v_pk_fma_f32 v[14:15], v[234:235], s[92:93], v[14:15] op_sel_hi:[1,0,1]
	v_pk_fma_f32 v[8:9], v[238:239], s[92:93], v[8:9] op_sel_hi:[1,0,1]
	v_pk_fma_f32 v[10:11], v[236:237], s[92:93], v[10:11] op_sel_hi:[1,0,1]
	v_cvt_pk_bf16_f32 v12, v12, v13
	v_cvt_pk_bf16_f32 v13, v14, v15
	v_cvt_pk_bf16_f32 v14, v8, v9
	v_cvt_pk_bf16_f32 v15, v10, v11
	global_store_dwordx4 v138, v[12:15], s[36:37] offset:256
	s_waitcnt vmcnt(15)
	v_lshlrev_b32_e32 v182, 16, v240
	v_and_b32_e32 v183, 0xffff0000, v240
	v_lshlrev_b32_e32 v240, 16, v241
	v_and_b32_e32 v241, 0xffff0000, v241
	v_lshlrev_b32_e32 v238, 16, v242
	v_and_b32_e32 v239, 0xffff0000, v242
	v_lshlrev_b32_e32 v242, 16, v243
	v_and_b32_e32 v243, 0xffff0000, v243
	v_pk_fma_f32 v[4:5], v[182:183], s[92:93], v[4:5] op_sel_hi:[1,0,1]
	v_pk_fma_f32 v[6:7], v[240:241], s[92:93], v[6:7] op_sel_hi:[1,0,1]
	v_pk_fma_f32 v[0:1], v[238:239], s[92:93], v[0:1] op_sel_hi:[1,0,1]
	v_pk_fma_f32 v[2:3], v[242:243], s[92:93], v[2:3] op_sel_hi:[1,0,1]
	v_cvt_pk_bf16_f32 v4, v4, v5
	v_cvt_pk_bf16_f32 v5, v6, v7
	v_cvt_pk_bf16_f32 v6, v0, v1
	v_cvt_pk_bf16_f32 v7, v2, v3
	global_store_dwordx4 v139, v[4:7], s[36:37] offset:256
	s_and_b64 vcc, exec, s[2:3]
	s_waitcnt vmcnt(22)
	s_cbranch_vccnz .LBB0_683
	s_branch .Lseam_res_l0

.LBB0_762:
	v_add_u32_e32 v134, s12, v150
	v_ashrrev_i32_e32 v135, 31, v134
	v_bfe_u32 v176, v187, 4, 1
	v_lshl_add_u64 v[132:133], s[14:15], 1, v[128:129]
	v_lshlrev_b64 v[160:161], 14, v[134:135]
	v_mul_u32_u24_e32 v176, 24, v176
	s_mov_b64 s[12:13], 0x40000
	v_or_b32_e32 v160, v160, v176
	v_lshl_add_u64 v[160:161], v[132:133], 0, v[160:161]
	v_lshl_add_u64 v[162:163], v[160:161], 0, s[12:13]
	v_lshl_add_u64 v[164:165], v[162:163], 0, s[12:13]
	v_lshl_add_u64 v[166:167], v[164:165], 0, s[12:13]
	s_mov_b64 s[12:13], 0x200000
	v_lshl_add_u64 v[168:169], v[160:161], 0, s[12:13]
	v_lshl_add_u64 v[170:171], v[162:163], 0, s[12:13]
	v_lshl_add_u64 v[172:173], v[164:165], 0, s[12:13]
	v_lshl_add_u64 v[174:175], v[166:167], 0, s[12:13]
	v_max_f32_e32 v124, 0, v124
	v_max_f32_e32 v125, 0, v125
	v_max_f32_e32 v126, 0, v126
	v_max_f32_e32 v127, 0, v127
	v_max_f32_e32 v120, 0, v120
	v_max_f32_e32 v121, 0, v121
	v_max_f32_e32 v122, 0, v122
	v_max_f32_e32 v123, 0, v123
	v_mul_f32_e32 v124, v124, v124
	v_mul_f32_e32 v125, v125, v125
	v_mul_f32_e32 v126, v126, v126
	v_mul_f32_e32 v127, v127, v127
	v_mul_f32_e32 v120, v120, v120
	v_mul_f32_e32 v121, v121, v121
	v_mul_f32_e32 v122, v122, v122
	v_mul_f32_e32 v123, v123, v123
	v_cvt_pk_bf16_f32 v124, v124, v125
	v_cvt_pk_bf16_f32 v125, v126, v127
	v_cvt_pk_bf16_f32 v126, v120, v121
	v_cvt_pk_bf16_f32 v127, v122, v123
	v_max_f32_e32 v116, 0, v116
	v_max_f32_e32 v117, 0, v117
	v_max_f32_e32 v118, 0, v118
	v_max_f32_e32 v119, 0, v119
	v_max_f32_e32 v112, 0, v112
	v_max_f32_e32 v113, 0, v113
	v_max_f32_e32 v114, 0, v114
	v_max_f32_e32 v115, 0, v115
	v_mul_f32_e32 v116, v116, v116
	v_mul_f32_e32 v117, v117, v117
	v_mul_f32_e32 v118, v118, v118
	v_mul_f32_e32 v119, v119, v119
	v_mul_f32_e32 v112, v112, v112
	v_mul_f32_e32 v113, v113, v113
	v_mul_f32_e32 v114, v114, v114
	v_mul_f32_e32 v115, v115, v115
	v_cvt_pk_bf16_f32 v116, v116, v117
	v_cvt_pk_bf16_f32 v117, v118, v119
	v_cvt_pk_bf16_f32 v118, v112, v113
	v_cvt_pk_bf16_f32 v119, v114, v115
	v_permlane16_swap_b32_e32 v124, v126
	v_permlane16_swap_b32_e32 v125, v127
	global_store_dwordx4 v[160:161], v[124:127], off
	v_max_f32_e32 v108, 0, v108
	v_max_f32_e32 v109, 0, v109
	v_max_f32_e32 v110, 0, v110
	v_max_f32_e32 v111, 0, v111
	v_max_f32_e32 v104, 0, v104
	v_max_f32_e32 v105, 0, v105
	v_max_f32_e32 v106, 0, v106
	v_max_f32_e32 v107, 0, v107
	v_mul_f32_e32 v108, v108, v108
	v_mul_f32_e32 v109, v109, v109
	v_mul_f32_e32 v110, v110, v110
	v_mul_f32_e32 v111, v111, v111
	v_mul_f32_e32 v104, v104, v104
	v_mul_f32_e32 v105, v105, v105
	v_mul_f32_e32 v106, v106, v106
	v_mul_f32_e32 v107, v107, v107
	v_cvt_pk_bf16_f32 v108, v108, v109
	v_cvt_pk_bf16_f32 v109, v110, v111
	v_cvt_pk_bf16_f32 v110, v104, v105
	v_cvt_pk_bf16_f32 v111, v106, v107
	v_permlane16_swap_b32_e32 v116, v118
	v_permlane16_swap_b32_e32 v117, v119
	global_store_dwordx4 v[162:163], v[116:119], off
	v_max_f32_e32 v100, 0, v100
	v_max_f32_e32 v101, 0, v101
	v_max_f32_e32 v102, 0, v102
	v_max_f32_e32 v103, 0, v103
	v_max_f32_e32 v96, 0, v96
	v_max_f32_e32 v97, 0, v97
	v_max_f32_e32 v98, 0, v98
	v_max_f32_e32 v99, 0, v99
	v_mul_f32_e32 v100, v100, v100
	v_mul_f32_e32 v101, v101, v101
	v_mul_f32_e32 v102, v102, v102
	v_mul_f32_e32 v103, v103, v103
	v_mul_f32_e32 v96, v96, v96
	v_mul_f32_e32 v97, v97, v97
	v_mul_f32_e32 v98, v98, v98
	v_mul_f32_e32 v99, v99, v99
	v_cvt_pk_bf16_f32 v100, v100, v101
	v_cvt_pk_bf16_f32 v101, v102, v103
	v_cvt_pk_bf16_f32 v102, v96, v97
	v_cvt_pk_bf16_f32 v103, v98, v99
	v_permlane16_swap_b32_e32 v108, v110
	v_permlane16_swap_b32_e32 v109, v111
	global_store_dwordx4 v[164:165], v[108:111], off
	v_max_f32_e32 v92, 0, v92
	v_max_f32_e32 v93, 0, v93
	v_max_f32_e32 v94, 0, v94
	v_max_f32_e32 v95, 0, v95
	v_max_f32_e32 v88, 0, v88
	v_max_f32_e32 v89, 0, v89
	v_max_f32_e32 v90, 0, v90
	v_max_f32_e32 v91, 0, v91
	v_mul_f32_e32 v92, v92, v92
	v_mul_f32_e32 v93, v93, v93
	v_mul_f32_e32 v94, v94, v94
	v_mul_f32_e32 v95, v95, v95
	v_mul_f32_e32 v88, v88, v88
	v_mul_f32_e32 v89, v89, v89
	v_mul_f32_e32 v90, v90, v90
	v_mul_f32_e32 v91, v91, v91
	v_cvt_pk_bf16_f32 v92, v92, v93
	v_cvt_pk_bf16_f32 v93, v94, v95
	v_cvt_pk_bf16_f32 v94, v88, v89
	v_cvt_pk_bf16_f32 v95, v90, v91
	v_permlane16_swap_b32_e32 v100, v102
	v_permlane16_swap_b32_e32 v101, v103
	global_store_dwordx4 v[166:167], v[100:103], off
	v_max_f32_e32 v84, 0, v84
	v_max_f32_e32 v85, 0, v85
	v_max_f32_e32 v86, 0, v86
	v_max_f32_e32 v87, 0, v87
	v_max_f32_e32 v80, 0, v80
	v_max_f32_e32 v81, 0, v81
	v_max_f32_e32 v82, 0, v82
	v_max_f32_e32 v83, 0, v83
	v_mul_f32_e32 v84, v84, v84
	v_mul_f32_e32 v85, v85, v85
	v_mul_f32_e32 v86, v86, v86
	v_mul_f32_e32 v87, v87, v87
	v_mul_f32_e32 v80, v80, v80
	v_mul_f32_e32 v81, v81, v81
	v_mul_f32_e32 v82, v82, v82
	v_mul_f32_e32 v83, v83, v83
	v_cvt_pk_bf16_f32 v84, v84, v85
	v_cvt_pk_bf16_f32 v85, v86, v87
	v_cvt_pk_bf16_f32 v86, v80, v81
	v_cvt_pk_bf16_f32 v87, v82, v83
	v_permlane16_swap_b32_e32 v92, v94
	v_permlane16_swap_b32_e32 v93, v95
	global_store_dwordx4 v[160:161], v[92:95], off offset:256
	v_max_f32_e32 v76, 0, v76
	v_max_f32_e32 v77, 0, v77
	v_max_f32_e32 v78, 0, v78
	v_max_f32_e32 v79, 0, v79
	v_max_f32_e32 v72, 0, v72
	v_max_f32_e32 v73, 0, v73
	v_max_f32_e32 v74, 0, v74
	v_max_f32_e32 v75, 0, v75
	v_mul_f32_e32 v76, v76, v76
	v_mul_f32_e32 v77, v77, v77
	v_mul_f32_e32 v78, v78, v78
	v_mul_f32_e32 v79, v79, v79
	v_mul_f32_e32 v72, v72, v72
	v_mul_f32_e32 v73, v73, v73
	v_mul_f32_e32 v74, v74, v74
	v_mul_f32_e32 v75, v75, v75
	v_cvt_pk_bf16_f32 v76, v76, v77
	v_cvt_pk_bf16_f32 v77, v78, v79
	v_cvt_pk_bf16_f32 v78, v72, v73
	v_cvt_pk_bf16_f32 v79, v74, v75
	v_permlane16_swap_b32_e32 v84, v86
	v_permlane16_swap_b32_e32 v85, v87
	global_store_dwordx4 v[162:163], v[84:87], off offset:256
	v_max_f32_e32 v68, 0, v68
	v_max_f32_e32 v69, 0, v69
	v_max_f32_e32 v70, 0, v70
	v_max_f32_e32 v71, 0, v71
	v_max_f32_e32 v64, 0, v64
	v_max_f32_e32 v65, 0, v65
	v_max_f32_e32 v66, 0, v66
	v_max_f32_e32 v67, 0, v67
	v_mul_f32_e32 v68, v68, v68
	v_mul_f32_e32 v69, v69, v69
	v_mul_f32_e32 v70, v70, v70
	v_mul_f32_e32 v71, v71, v71
	v_mul_f32_e32 v64, v64, v64
	v_mul_f32_e32 v65, v65, v65
	v_mul_f32_e32 v66, v66, v66
	v_mul_f32_e32 v67, v67, v67
	v_cvt_pk_bf16_f32 v68, v68, v69
	v_cvt_pk_bf16_f32 v69, v70, v71
	v_cvt_pk_bf16_f32 v70, v64, v65
	v_cvt_pk_bf16_f32 v71, v66, v67
	v_permlane16_swap_b32_e32 v76, v78
	v_permlane16_swap_b32_e32 v77, v79
	global_store_dwordx4 v[164:165], v[76:79], off offset:256
	v_max_f32_e32 v60, 0, v60
	v_max_f32_e32 v61, 0, v61
	v_max_f32_e32 v62, 0, v62
	v_max_f32_e32 v63, 0, v63
	v_max_f32_e32 v56, 0, v56
	v_max_f32_e32 v57, 0, v57
	v_max_f32_e32 v58, 0, v58
	v_max_f32_e32 v59, 0, v59
	v_mul_f32_e32 v60, v60, v60
	v_mul_f32_e32 v61, v61, v61
	v_mul_f32_e32 v62, v62, v62
	v_mul_f32_e32 v63, v63, v63
	v_mul_f32_e32 v56, v56, v56
	v_mul_f32_e32 v57, v57, v57
	v_mul_f32_e32 v58, v58, v58
	v_mul_f32_e32 v59, v59, v59
	v_cvt_pk_bf16_f32 v60, v60, v61
	v_cvt_pk_bf16_f32 v61, v62, v63
	v_cvt_pk_bf16_f32 v62, v56, v57
	v_cvt_pk_bf16_f32 v63, v58, v59
	v_permlane16_swap_b32_e32 v68, v70
	v_permlane16_swap_b32_e32 v69, v71
	global_store_dwordx4 v[166:167], v[68:71], off offset:256
	v_max_f32_e32 v52, 0, v52
	v_max_f32_e32 v53, 0, v53
	v_max_f32_e32 v54, 0, v54
	v_max_f32_e32 v55, 0, v55
	v_max_f32_e32 v48, 0, v48
	v_max_f32_e32 v49, 0, v49
	v_max_f32_e32 v50, 0, v50
	v_max_f32_e32 v51, 0, v51
	v_mul_f32_e32 v52, v52, v52
	v_mul_f32_e32 v53, v53, v53
	v_mul_f32_e32 v54, v54, v54
	v_mul_f32_e32 v55, v55, v55
	v_mul_f32_e32 v48, v48, v48
	v_mul_f32_e32 v49, v49, v49
	v_mul_f32_e32 v50, v50, v50
	v_mul_f32_e32 v51, v51, v51
	v_cvt_pk_bf16_f32 v52, v52, v53
	v_cvt_pk_bf16_f32 v53, v54, v55
	v_cvt_pk_bf16_f32 v54, v48, v49
	v_cvt_pk_bf16_f32 v55, v50, v51
	v_permlane16_swap_b32_e32 v60, v62
	v_permlane16_swap_b32_e32 v61, v63
	global_store_dwordx4 v[168:169], v[60:63], off
	v_max_f32_e32 v44, 0, v44
	v_max_f32_e32 v45, 0, v45
	v_max_f32_e32 v46, 0, v46
	v_max_f32_e32 v47, 0, v47
	v_max_f32_e32 v40, 0, v40
	v_max_f32_e32 v41, 0, v41
	v_max_f32_e32 v42, 0, v42
	v_max_f32_e32 v43, 0, v43
	v_mul_f32_e32 v44, v44, v44
	v_mul_f32_e32 v45, v45, v45
	v_mul_f32_e32 v46, v46, v46
	v_mul_f32_e32 v47, v47, v47
	v_mul_f32_e32 v40, v40, v40
	v_mul_f32_e32 v41, v41, v41
	v_mul_f32_e32 v42, v42, v42
	v_mul_f32_e32 v43, v43, v43
	v_cvt_pk_bf16_f32 v44, v44, v45
	v_cvt_pk_bf16_f32 v45, v46, v47
	v_cvt_pk_bf16_f32 v46, v40, v41
	v_cvt_pk_bf16_f32 v47, v42, v43
	v_permlane16_swap_b32_e32 v52, v54
	v_permlane16_swap_b32_e32 v53, v55
	global_store_dwordx4 v[170:171], v[52:55], off
	v_max_f32_e32 v36, 0, v36
	v_max_f32_e32 v37, 0, v37
	v_max_f32_e32 v38, 0, v38
	v_max_f32_e32 v39, 0, v39
	v_max_f32_e32 v32, 0, v32
	v_max_f32_e32 v33, 0, v33
	v_max_f32_e32 v34, 0, v34
	v_max_f32_e32 v35, 0, v35
	v_mul_f32_e32 v36, v36, v36
	v_mul_f32_e32 v37, v37, v37
	v_mul_f32_e32 v38, v38, v38
	v_mul_f32_e32 v39, v39, v39
	v_mul_f32_e32 v32, v32, v32
	v_mul_f32_e32 v33, v33, v33
	v_mul_f32_e32 v34, v34, v34
	v_mul_f32_e32 v35, v35, v35
	v_cvt_pk_bf16_f32 v36, v36, v37
	v_cvt_pk_bf16_f32 v37, v38, v39
	v_cvt_pk_bf16_f32 v38, v32, v33
	v_cvt_pk_bf16_f32 v39, v34, v35
	v_permlane16_swap_b32_e32 v44, v46
	v_permlane16_swap_b32_e32 v45, v47
	global_store_dwordx4 v[172:173], v[44:47], off
	v_max_f32_e32 v28, 0, v28
	v_max_f32_e32 v29, 0, v29
	v_max_f32_e32 v30, 0, v30
	v_max_f32_e32 v31, 0, v31
	v_max_f32_e32 v24, 0, v24
	v_max_f32_e32 v25, 0, v25
	v_max_f32_e32 v26, 0, v26
	v_max_f32_e32 v27, 0, v27
	v_mul_f32_e32 v28, v28, v28
	v_mul_f32_e32 v29, v29, v29
	v_mul_f32_e32 v30, v30, v30
	v_mul_f32_e32 v31, v31, v31
	v_mul_f32_e32 v24, v24, v24
	v_mul_f32_e32 v25, v25, v25
	v_mul_f32_e32 v26, v26, v26
	v_mul_f32_e32 v27, v27, v27
	v_cvt_pk_bf16_f32 v28, v28, v29
	v_cvt_pk_bf16_f32 v29, v30, v31
	v_cvt_pk_bf16_f32 v30, v24, v25
	v_cvt_pk_bf16_f32 v31, v26, v27
	v_permlane16_swap_b32_e32 v36, v38
	v_permlane16_swap_b32_e32 v37, v39
	global_store_dwordx4 v[174:175], v[36:39], off
	v_max_f32_e32 v20, 0, v20
	v_max_f32_e32 v21, 0, v21
	v_max_f32_e32 v22, 0, v22
	v_max_f32_e32 v23, 0, v23
	v_max_f32_e32 v16, 0, v16
	v_max_f32_e32 v17, 0, v17
	v_max_f32_e32 v18, 0, v18
	v_max_f32_e32 v19, 0, v19
	v_mul_f32_e32 v20, v20, v20
	v_mul_f32_e32 v21, v21, v21
	v_mul_f32_e32 v22, v22, v22
	v_mul_f32_e32 v23, v23, v23
	v_mul_f32_e32 v16, v16, v16
	v_mul_f32_e32 v17, v17, v17
	v_mul_f32_e32 v18, v18, v18
	v_mul_f32_e32 v19, v19, v19
	v_cvt_pk_bf16_f32 v20, v20, v21
	v_cvt_pk_bf16_f32 v21, v22, v23
	v_cvt_pk_bf16_f32 v22, v16, v17
	v_cvt_pk_bf16_f32 v23, v18, v19
	v_permlane16_swap_b32_e32 v28, v30
	v_permlane16_swap_b32_e32 v29, v31
	global_store_dwordx4 v[168:169], v[28:31], off offset:256
	v_max_f32_e32 v12, 0, v12
	v_max_f32_e32 v13, 0, v13
	v_max_f32_e32 v14, 0, v14
	v_max_f32_e32 v15, 0, v15
	v_max_f32_e32 v8, 0, v8
	v_max_f32_e32 v9, 0, v9
	v_max_f32_e32 v10, 0, v10
	v_max_f32_e32 v11, 0, v11
	v_mul_f32_e32 v12, v12, v12
	v_mul_f32_e32 v13, v13, v13
	v_mul_f32_e32 v14, v14, v14
	v_mul_f32_e32 v15, v15, v15
	v_mul_f32_e32 v8, v8, v8
	v_mul_f32_e32 v9, v9, v9
	v_mul_f32_e32 v10, v10, v10
	v_mul_f32_e32 v11, v11, v11
	v_cvt_pk_bf16_f32 v12, v12, v13
	v_cvt_pk_bf16_f32 v13, v14, v15
	v_cvt_pk_bf16_f32 v14, v8, v9
	v_cvt_pk_bf16_f32 v15, v10, v11
	v_permlane16_swap_b32_e32 v20, v22
	v_permlane16_swap_b32_e32 v21, v23
	global_store_dwordx4 v[170:171], v[20:23], off offset:256
	v_max_f32_e32 v4, 0, v4
	v_max_f32_e32 v5, 0, v5
	v_max_f32_e32 v6, 0, v6
	v_max_f32_e32 v7, 0, v7
	v_max_f32_e32 v0, 0, v0
	v_max_f32_e32 v1, 0, v1
	v_max_f32_e32 v2, 0, v2
	v_max_f32_e32 v3, 0, v3
	v_mul_f32_e32 v4, v4, v4
	v_mul_f32_e32 v5, v5, v5
	v_mul_f32_e32 v6, v6, v6
	v_mul_f32_e32 v7, v7, v7
	v_mul_f32_e32 v0, v0, v0
	v_mul_f32_e32 v1, v1, v1
	v_mul_f32_e32 v2, v2, v2
	v_mul_f32_e32 v3, v3, v3
	v_cvt_pk_bf16_f32 v4, v4, v5
	v_cvt_pk_bf16_f32 v5, v6, v7
	v_cvt_pk_bf16_f32 v6, v0, v1
	v_cvt_pk_bf16_f32 v7, v2, v3
	v_permlane16_swap_b32_e32 v12, v14
	v_permlane16_swap_b32_e32 v13, v15
	global_store_dwordx4 v[172:173], v[12:15], off offset:256
	s_nop 1
	v_permlane16_swap_b32_e32 v4, v6
	v_permlane16_swap_b32_e32 v5, v7
	global_store_dwordx4 v[174:175], v[4:7], off offset:256
	s_mov_b32 s11, 0x40000
	s_mov_b32 s13, 0xc0000
	s_mov_b32 s12, s18
	s_andn2_b64 vcc, exec, s[16:17]
	s_waitcnt vmcnt(38)
	s_cbranch_vccz .LBB0_771
	s_branch .Lseam_up

.LBB0_811:
	v_add_u32_e32 v182, s14, v153
	v_or_b32_e32 v183, s16, v128
	s_mov_b32 s14, s64
	v_bfe_u32 v238, v187, 4, 1
	v_lshl_add_u32 v182, v182, 11, v183
	v_mul_u32_u24_e32 v238, 24, v238
	v_lshl_add_u32 v132, v182, 1, v238
	v_add_u32_e32 v133, 0x10000, v132
	v_add_u32_e32 v134, 0x20000, v132
	v_add_u32_e32 v135, 0x30000, v132
	v_add_u32_e32 v136, 0x80000, v132
	v_add_u32_e32 v137, 0x90000, v132
	v_add_u32_e32 v138, 0xa0000, v132
	v_add_u32_e32 v139, 0xb0000, v132
	global_load_dwordx4 v[162:165], v132, s[34:35]
	global_load_dwordx4 v[166:169], v133, s[34:35]
	global_load_dwordx4 v[170:173], v134, s[34:35]
	global_load_dwordx4 v[174:177], v135, s[34:35]
	global_load_dwordx4 v[178:181], v132, s[34:35] offset:256
	global_load_dwordx4 v[190:193], v133, s[34:35] offset:256
	global_load_dwordx4 v[194:197], v134, s[34:35] offset:256
	global_load_dwordx4 v[206:209], v135, s[34:35] offset:256
	global_load_dwordx4 v[210:213], v136, s[34:35]
	global_load_dwordx4 v[214:217], v137, s[34:35]
	global_load_dwordx4 v[218:221], v138, s[34:35]
	global_load_dwordx4 v[222:225], v139, s[34:35]
	global_load_dwordx4 v[226:229], v136, s[34:35] offset:256
	global_load_dwordx4 v[230:233], v137, s[34:35] offset:256
	global_load_dwordx4 v[234:237], v138, s[34:35] offset:256
	global_load_dwordx4 v[240:243], v139, s[34:35] offset:256
	v_permlane16_swap_b32_e32 v124, v120
	v_permlane16_swap_b32_e32 v125, v121
	v_permlane16_swap_b32_e32 v126, v122
	v_permlane16_swap_b32_e32 v127, v123
	v_permlane16_swap_b32_e32 v116, v112
	v_permlane16_swap_b32_e32 v117, v113
	v_permlane16_swap_b32_e32 v118, v114
	v_permlane16_swap_b32_e32 v119, v115
	v_permlane16_swap_b32_e32 v108, v104
	v_permlane16_swap_b32_e32 v109, v105
	v_permlane16_swap_b32_e32 v110, v106
	v_permlane16_swap_b32_e32 v111, v107
	v_permlane16_swap_b32_e32 v100, v96
	v_permlane16_swap_b32_e32 v101, v97
	v_permlane16_swap_b32_e32 v102, v98
	v_permlane16_swap_b32_e32 v103, v99
	v_permlane16_swap_b32_e32 v92, v88
	v_permlane16_swap_b32_e32 v93, v89
	v_permlane16_swap_b32_e32 v94, v90
	v_permlane16_swap_b32_e32 v95, v91
	v_permlane16_swap_b32_e32 v84, v80
	v_permlane16_swap_b32_e32 v85, v81
	v_permlane16_swap_b32_e32 v86, v82
	v_permlane16_swap_b32_e32 v87, v83
	v_permlane16_swap_b32_e32 v76, v72
	v_permlane16_swap_b32_e32 v77, v73
	v_permlane16_swap_b32_e32 v78, v74
	v_permlane16_swap_b32_e32 v79, v75
	v_permlane16_swap_b32_e32 v68, v64
	v_permlane16_swap_b32_e32 v69, v65
	v_permlane16_swap_b32_e32 v70, v66
	v_permlane16_swap_b32_e32 v71, v67
	v_permlane16_swap_b32_e32 v60, v56
	v_permlane16_swap_b32_e32 v61, v57
	v_permlane16_swap_b32_e32 v62, v58
	v_permlane16_swap_b32_e32 v63, v59
	v_permlane16_swap_b32_e32 v52, v48
	v_permlane16_swap_b32_e32 v53, v49
	v_permlane16_swap_b32_e32 v54, v50
	v_permlane16_swap_b32_e32 v55, v51
	v_permlane16_swap_b32_e32 v44, v40
	v_permlane16_swap_b32_e32 v45, v41
	v_permlane16_swap_b32_e32 v46, v42
	v_permlane16_swap_b32_e32 v47, v43
	v_permlane16_swap_b32_e32 v36, v32
	v_permlane16_swap_b32_e32 v37, v33
	v_permlane16_swap_b32_e32 v38, v34
	v_permlane16_swap_b32_e32 v39, v35
	v_permlane16_swap_b32_e32 v28, v24
	v_permlane16_swap_b32_e32 v29, v25
	v_permlane16_swap_b32_e32 v30, v26
	v_permlane16_swap_b32_e32 v31, v27
	v_permlane16_swap_b32_e32 v20, v16
	v_permlane16_swap_b32_e32 v21, v17
	v_permlane16_swap_b32_e32 v22, v18
	v_permlane16_swap_b32_e32 v23, v19
	v_permlane16_swap_b32_e32 v12, v8
	v_permlane16_swap_b32_e32 v13, v9
	v_permlane16_swap_b32_e32 v14, v10
	v_permlane16_swap_b32_e32 v15, v11
	v_permlane16_swap_b32_e32 v4, v0
	v_permlane16_swap_b32_e32 v5, v1
	v_permlane16_swap_b32_e32 v6, v2
	v_permlane16_swap_b32_e32 v7, v3
	s_waitcnt vmcnt(15)
	v_lshlrev_b32_e32 v182, 16, v162
	v_and_b32_e32 v183, 0xffff0000, v162
	v_lshlrev_b32_e32 v162, 16, v163
	v_and_b32_e32 v163, 0xffff0000, v163
	v_lshlrev_b32_e32 v238, 16, v164
	v_and_b32_e32 v239, 0xffff0000, v164
	v_lshlrev_b32_e32 v164, 16, v165
	v_and_b32_e32 v165, 0xffff0000, v165
	v_pk_fma_f32 v[124:125], v[182:183], s[92:93], v[124:125] op_sel_hi:[1,0,1]
	v_pk_fma_f32 v[126:127], v[162:163], s[92:93], v[126:127] op_sel_hi:[1,0,1]
	v_pk_fma_f32 v[120:121], v[238:239], s[92:93], v[120:121] op_sel_hi:[1,0,1]
	v_pk_fma_f32 v[122:123], v[164:165], s[92:93], v[122:123] op_sel_hi:[1,0,1]
	v_cvt_pk_bf16_f32 v124, v124, v125
	v_cvt_pk_bf16_f32 v125, v126, v127
	v_cvt_pk_bf16_f32 v126, v120, v121
	v_cvt_pk_bf16_f32 v127, v122, v123
	global_store_dwordx4 v132, v[124:127], s[10:11]
	s_waitcnt vmcnt(15)
	v_lshlrev_b32_e32 v182, 16, v166
	v_and_b32_e32 v183, 0xffff0000, v166
	v_lshlrev_b32_e32 v166, 16, v167
	v_and_b32_e32 v167, 0xffff0000, v167
	v_lshlrev_b32_e32 v238, 16, v168
	v_and_b32_e32 v239, 0xffff0000, v168
	v_lshlrev_b32_e32 v168, 16, v169
	v_and_b32_e32 v169, 0xffff0000, v169
	v_pk_fma_f32 v[116:117], v[182:183], s[92:93], v[116:117] op_sel_hi:[1,0,1]
	v_pk_fma_f32 v[118:119], v[166:167], s[92:93], v[118:119] op_sel_hi:[1,0,1]
	v_pk_fma_f32 v[112:113], v[238:239], s[92:93], v[112:113] op_sel_hi:[1,0,1]
	v_pk_fma_f32 v[114:115], v[168:169], s[92:93], v[114:115] op_sel_hi:[1,0,1]
	v_cvt_pk_bf16_f32 v116, v116, v117
	v_cvt_pk_bf16_f32 v117, v118, v119
	v_cvt_pk_bf16_f32 v118, v112, v113
	v_cvt_pk_bf16_f32 v119, v114, v115
	global_store_dwordx4 v133, v[116:119], s[10:11]
	s_waitcnt vmcnt(15)
	v_lshlrev_b32_e32 v182, 16, v170
	v_and_b32_e32 v183, 0xffff0000, v170
	v_lshlrev_b32_e32 v170, 16, v171
	v_and_b32_e32 v171, 0xffff0000, v171
	v_lshlrev_b32_e32 v238, 16, v172
	v_and_b32_e32 v239, 0xffff0000, v172
	v_lshlrev_b32_e32 v172, 16, v173
	v_and_b32_e32 v173, 0xffff0000, v173
	v_pk_fma_f32 v[108:109], v[182:183], s[92:93], v[108:109] op_sel_hi:[1,0,1]
	v_pk_fma_f32 v[110:111], v[170:171], s[92:93], v[110:111] op_sel_hi:[1,0,1]
	v_pk_fma_f32 v[104:105], v[238:239], s[92:93], v[104:105] op_sel_hi:[1,0,1]
	v_pk_fma_f32 v[106:107], v[172:173], s[92:93], v[106:107] op_sel_hi:[1,0,1]
	v_cvt_pk_bf16_f32 v108, v108, v109
	v_cvt_pk_bf16_f32 v109, v110, v111
	v_cvt_pk_bf16_f32 v110, v104, v105
	v_cvt_pk_bf16_f32 v111, v106, v107
	global_store_dwordx4 v134, v[108:111], s[10:11]
	s_waitcnt vmcnt(15)
	v_lshlrev_b32_e32 v182, 16, v174
	v_and_b32_e32 v183, 0xffff0000, v174
	v_lshlrev_b32_e32 v174, 16, v175
	v_and_b32_e32 v175, 0xffff0000, v175
	v_lshlrev_b32_e32 v238, 16, v176
	v_and_b32_e32 v239, 0xffff0000, v176
	v_lshlrev_b32_e32 v176, 16, v177
	v_and_b32_e32 v177, 0xffff0000, v177
	v_pk_fma_f32 v[100:101], v[182:183], s[92:93], v[100:101] op_sel_hi:[1,0,1]
	v_pk_fma_f32 v[102:103], v[174:175], s[92:93], v[102:103] op_sel_hi:[1,0,1]
	v_pk_fma_f32 v[96:97], v[238:239], s[92:93], v[96:97] op_sel_hi:[1,0,1]
	v_pk_fma_f32 v[98:99], v[176:177], s[92:93], v[98:99] op_sel_hi:[1,0,1]
	v_cvt_pk_bf16_f32 v100, v100, v101
	v_cvt_pk_bf16_f32 v101, v102, v103
	v_cvt_pk_bf16_f32 v102, v96, v97
	v_cvt_pk_bf16_f32 v103, v98, v99
	global_store_dwordx4 v135, v[100:103], s[10:11]
	s_waitcnt vmcnt(15)
	v_lshlrev_b32_e32 v182, 16, v178
	v_and_b32_e32 v183, 0xffff0000, v178
	v_lshlrev_b32_e32 v178, 16, v179
	v_and_b32_e32 v179, 0xffff0000, v179
	v_lshlrev_b32_e32 v238, 16, v180
	v_and_b32_e32 v239, 0xffff0000, v180
	v_lshlrev_b32_e32 v180, 16, v181
	v_and_b32_e32 v181, 0xffff0000, v181
	v_pk_fma_f32 v[92:93], v[182:183], s[92:93], v[92:93] op_sel_hi:[1,0,1]
	v_pk_fma_f32 v[94:95], v[178:179], s[92:93], v[94:95] op_sel_hi:[1,0,1]
	v_pk_fma_f32 v[88:89], v[238:239], s[92:93], v[88:89] op_sel_hi:[1,0,1]
	v_pk_fma_f32 v[90:91], v[180:181], s[92:93], v[90:91] op_sel_hi:[1,0,1]
	v_cvt_pk_bf16_f32 v92, v92, v93
	v_cvt_pk_bf16_f32 v93, v94, v95
	v_cvt_pk_bf16_f32 v94, v88, v89
	v_cvt_pk_bf16_f32 v95, v90, v91
	global_store_dwordx4 v132, v[92:95], s[10:11] offset:256
	s_waitcnt vmcnt(15)
	v_lshlrev_b32_e32 v182, 16, v190
	v_and_b32_e32 v183, 0xffff0000, v190
	v_lshlrev_b32_e32 v190, 16, v191
	v_and_b32_e32 v191, 0xffff0000, v191
	v_lshlrev_b32_e32 v238, 16, v192
	v_and_b32_e32 v239, 0xffff0000, v192
	v_lshlrev_b32_e32 v192, 16, v193
	v_and_b32_e32 v193, 0xffff0000, v193
	v_pk_fma_f32 v[84:85], v[182:183], s[92:93], v[84:85] op_sel_hi:[1,0,1]
	v_pk_fma_f32 v[86:87], v[190:191], s[92:93], v[86:87] op_sel_hi:[1,0,1]
	v_pk_fma_f32 v[80:81], v[238:239], s[92:93], v[80:81] op_sel_hi:[1,0,1]
	v_pk_fma_f32 v[82:83], v[192:193], s[92:93], v[82:83] op_sel_hi:[1,0,1]
	v_cvt_pk_bf16_f32 v84, v84, v85
	v_cvt_pk_bf16_f32 v85, v86, v87
	v_cvt_pk_bf16_f32 v86, v80, v81
	v_cvt_pk_bf16_f32 v87, v82, v83
	global_store_dwordx4 v133, v[84:87], s[10:11] offset:256
	s_waitcnt vmcnt(15)
	v_lshlrev_b32_e32 v182, 16, v194
	v_and_b32_e32 v183, 0xffff0000, v194
	v_lshlrev_b32_e32 v194, 16, v195
	v_and_b32_e32 v195, 0xffff0000, v195
	v_lshlrev_b32_e32 v238, 16, v196
	v_and_b32_e32 v239, 0xffff0000, v196
	v_lshlrev_b32_e32 v196, 16, v197
	v_and_b32_e32 v197, 0xffff0000, v197
	v_pk_fma_f32 v[76:77], v[182:183], s[92:93], v[76:77] op_sel_hi:[1,0,1]
	v_pk_fma_f32 v[78:79], v[194:195], s[92:93], v[78:79] op_sel_hi:[1,0,1]
	v_pk_fma_f32 v[72:73], v[238:239], s[92:93], v[72:73] op_sel_hi:[1,0,1]
	v_pk_fma_f32 v[74:75], v[196:197], s[92:93], v[74:75] op_sel_hi:[1,0,1]
	v_cvt_pk_bf16_f32 v76, v76, v77
	v_cvt_pk_bf16_f32 v77, v78, v79
	v_cvt_pk_bf16_f32 v78, v72, v73
	v_cvt_pk_bf16_f32 v79, v74, v75
	global_store_dwordx4 v134, v[76:79], s[10:11] offset:256
	s_waitcnt vmcnt(15)
	v_lshlrev_b32_e32 v182, 16, v206
	v_and_b32_e32 v183, 0xffff0000, v206
	v_lshlrev_b32_e32 v206, 16, v207
	v_and_b32_e32 v207, 0xffff0000, v207
	v_lshlrev_b32_e32 v238, 16, v208
	v_and_b32_e32 v239, 0xffff0000, v208
	v_lshlrev_b32_e32 v208, 16, v209
	v_and_b32_e32 v209, 0xffff0000, v209
	v_pk_fma_f32 v[68:69], v[182:183], s[92:93], v[68:69] op_sel_hi:[1,0,1]
	v_pk_fma_f32 v[70:71], v[206:207], s[92:93], v[70:71] op_sel_hi:[1,0,1]
	v_pk_fma_f32 v[64:65], v[238:239], s[92:93], v[64:65] op_sel_hi:[1,0,1]
	v_pk_fma_f32 v[66:67], v[208:209], s[92:93], v[66:67] op_sel_hi:[1,0,1]
	v_cvt_pk_bf16_f32 v68, v68, v69
	v_cvt_pk_bf16_f32 v69, v70, v71
	v_cvt_pk_bf16_f32 v70, v64, v65
	v_cvt_pk_bf16_f32 v71, v66, v67
	global_store_dwordx4 v135, v[68:71], s[10:11] offset:256
	s_waitcnt vmcnt(15)
	v_lshlrev_b32_e32 v182, 16, v210
	v_and_b32_e32 v183, 0xffff0000, v210
	v_lshlrev_b32_e32 v210, 16, v211
	v_and_b32_e32 v211, 0xffff0000, v211
	v_lshlrev_b32_e32 v238, 16, v212
	v_and_b32_e32 v239, 0xffff0000, v212
	v_lshlrev_b32_e32 v212, 16, v213
	v_and_b32_e32 v213, 0xffff0000, v213
	v_pk_fma_f32 v[60:61], v[182:183], s[92:93], v[60:61] op_sel_hi:[1,0,1]
	v_pk_fma_f32 v[62:63], v[210:211], s[92:93], v[62:63] op_sel_hi:[1,0,1]
	v_pk_fma_f32 v[56:57], v[238:239], s[92:93], v[56:57] op_sel_hi:[1,0,1]
	v_pk_fma_f32 v[58:59], v[212:213], s[92:93], v[58:59] op_sel_hi:[1,0,1]
	v_cvt_pk_bf16_f32 v60, v60, v61
	v_cvt_pk_bf16_f32 v61, v62, v63
	v_cvt_pk_bf16_f32 v62, v56, v57
	v_cvt_pk_bf16_f32 v63, v58, v59
	global_store_dwordx4 v136, v[60:63], s[10:11]
	s_waitcnt vmcnt(15)
	v_lshlrev_b32_e32 v182, 16, v214
	v_and_b32_e32 v183, 0xffff0000, v214
	v_lshlrev_b32_e32 v214, 16, v215
	v_and_b32_e32 v215, 0xffff0000, v215
	v_lshlrev_b32_e32 v238, 16, v216
	v_and_b32_e32 v239, 0xffff0000, v216
	v_lshlrev_b32_e32 v216, 16, v217
	v_and_b32_e32 v217, 0xffff0000, v217
	v_pk_fma_f32 v[52:53], v[182:183], s[92:93], v[52:53] op_sel_hi:[1,0,1]
	v_pk_fma_f32 v[54:55], v[214:215], s[92:93], v[54:55] op_sel_hi:[1,0,1]
	v_pk_fma_f32 v[48:49], v[238:239], s[92:93], v[48:49] op_sel_hi:[1,0,1]
	v_pk_fma_f32 v[50:51], v[216:217], s[92:93], v[50:51] op_sel_hi:[1,0,1]
	v_cvt_pk_bf16_f32 v52, v52, v53
	v_cvt_pk_bf16_f32 v53, v54, v55
	v_cvt_pk_bf16_f32 v54, v48, v49
	v_cvt_pk_bf16_f32 v55, v50, v51
	global_store_dwordx4 v137, v[52:55], s[10:11]
	s_waitcnt vmcnt(15)
	v_lshlrev_b32_e32 v182, 16, v218
	v_and_b32_e32 v183, 0xffff0000, v218
	v_lshlrev_b32_e32 v218, 16, v219
	v_and_b32_e32 v219, 0xffff0000, v219
	v_lshlrev_b32_e32 v238, 16, v220
	v_and_b32_e32 v239, 0xffff0000, v220
	v_lshlrev_b32_e32 v220, 16, v221
	v_and_b32_e32 v221, 0xffff0000, v221
	v_pk_fma_f32 v[44:45], v[182:183], s[92:93], v[44:45] op_sel_hi:[1,0,1]
	v_pk_fma_f32 v[46:47], v[218:219], s[92:93], v[46:47] op_sel_hi:[1,0,1]
	v_pk_fma_f32 v[40:41], v[238:239], s[92:93], v[40:41] op_sel_hi:[1,0,1]
	v_pk_fma_f32 v[42:43], v[220:221], s[92:93], v[42:43] op_sel_hi:[1,0,1]
	v_cvt_pk_bf16_f32 v44, v44, v45
	v_cvt_pk_bf16_f32 v45, v46, v47
	v_cvt_pk_bf16_f32 v46, v40, v41
	v_cvt_pk_bf16_f32 v47, v42, v43
	global_store_dwordx4 v138, v[44:47], s[10:11]
	s_waitcnt vmcnt(15)
	v_lshlrev_b32_e32 v182, 16, v222
	v_and_b32_e32 v183, 0xffff0000, v222
	v_lshlrev_b32_e32 v222, 16, v223
	v_and_b32_e32 v223, 0xffff0000, v223
	v_lshlrev_b32_e32 v238, 16, v224
	v_and_b32_e32 v239, 0xffff0000, v224
	v_lshlrev_b32_e32 v224, 16, v225
	v_and_b32_e32 v225, 0xffff0000, v225
	v_pk_fma_f32 v[36:37], v[182:183], s[92:93], v[36:37] op_sel_hi:[1,0,1]
	v_pk_fma_f32 v[38:39], v[222:223], s[92:93], v[38:39] op_sel_hi:[1,0,1]
	v_pk_fma_f32 v[32:33], v[238:239], s[92:93], v[32:33] op_sel_hi:[1,0,1]
	v_pk_fma_f32 v[34:35], v[224:225], s[92:93], v[34:35] op_sel_hi:[1,0,1]
	v_cvt_pk_bf16_f32 v36, v36, v37
	v_cvt_pk_bf16_f32 v37, v38, v39
	v_cvt_pk_bf16_f32 v38, v32, v33
	v_cvt_pk_bf16_f32 v39, v34, v35
	global_store_dwordx4 v139, v[36:39], s[10:11]
	s_waitcnt vmcnt(15)
	v_lshlrev_b32_e32 v182, 16, v226
	v_and_b32_e32 v183, 0xffff0000, v226
	v_lshlrev_b32_e32 v226, 16, v227
	v_and_b32_e32 v227, 0xffff0000, v227
	v_lshlrev_b32_e32 v238, 16, v228
	v_and_b32_e32 v239, 0xffff0000, v228
	v_lshlrev_b32_e32 v228, 16, v229
	v_and_b32_e32 v229, 0xffff0000, v229
	v_pk_fma_f32 v[28:29], v[182:183], s[92:93], v[28:29] op_sel_hi:[1,0,1]
	v_pk_fma_f32 v[30:31], v[226:227], s[92:93], v[30:31] op_sel_hi:[1,0,1]
	v_pk_fma_f32 v[24:25], v[238:239], s[92:93], v[24:25] op_sel_hi:[1,0,1]
	v_pk_fma_f32 v[26:27], v[228:229], s[92:93], v[26:27] op_sel_hi:[1,0,1]
	v_cvt_pk_bf16_f32 v28, v28, v29
	v_cvt_pk_bf16_f32 v29, v30, v31
	v_cvt_pk_bf16_f32 v30, v24, v25
	v_cvt_pk_bf16_f32 v31, v26, v27
	global_store_dwordx4 v136, v[28:31], s[10:11] offset:256
	s_waitcnt vmcnt(15)
	v_lshlrev_b32_e32 v182, 16, v230
	v_and_b32_e32 v183, 0xffff0000, v230
	v_lshlrev_b32_e32 v230, 16, v231
	v_and_b32_e32 v231, 0xffff0000, v231
	v_lshlrev_b32_e32 v238, 16, v232
	v_and_b32_e32 v239, 0xffff0000, v232
	v_lshlrev_b32_e32 v232, 16, v233
	v_and_b32_e32 v233, 0xffff0000, v233
	v_pk_fma_f32 v[20:21], v[182:183], s[92:93], v[20:21] op_sel_hi:[1,0,1]
	v_pk_fma_f32 v[22:23], v[230:231], s[92:93], v[22:23] op_sel_hi:[1,0,1]
	v_pk_fma_f32 v[16:17], v[238:239], s[92:93], v[16:17] op_sel_hi:[1,0,1]
	v_pk_fma_f32 v[18:19], v[232:233], s[92:93], v[18:19] op_sel_hi:[1,0,1]
	v_cvt_pk_bf16_f32 v20, v20, v21
	v_cvt_pk_bf16_f32 v21, v22, v23
	v_cvt_pk_bf16_f32 v22, v16, v17
	v_cvt_pk_bf16_f32 v23, v18, v19
	global_store_dwordx4 v137, v[20:23], s[10:11] offset:256
	s_waitcnt vmcnt(15)
	v_lshlrev_b32_e32 v182, 16, v234
	v_and_b32_e32 v183, 0xffff0000, v234
	v_lshlrev_b32_e32 v234, 16, v235
	v_and_b32_e32 v235, 0xffff0000, v235
	v_lshlrev_b32_e32 v238, 16, v236
	v_and_b32_e32 v239, 0xffff0000, v236
	v_lshlrev_b32_e32 v236, 16, v237
	v_and_b32_e32 v237, 0xffff0000, v237
	v_pk_fma_f32 v[12:13], v[182:183], s[92:93], v[12:13] op_sel_hi:[1,0,1]
	v_pk_fma_f32 v[14:15], v[234:235], s[92:93], v[14:15] op_sel_hi:[1,0,1]
	v_pk_fma_f32 v[8:9], v[238:239], s[92:93], v[8:9] op_sel_hi:[1,0,1]
	v_pk_fma_f32 v[10:11], v[236:237], s[92:93], v[10:11] op_sel_hi:[1,0,1]
	v_cvt_pk_bf16_f32 v12, v12, v13
	v_cvt_pk_bf16_f32 v13, v14, v15
	v_cvt_pk_bf16_f32 v14, v8, v9
	v_cvt_pk_bf16_f32 v15, v10, v11
	global_store_dwordx4 v138, v[12:15], s[10:11] offset:256
	s_waitcnt vmcnt(15)
	v_lshlrev_b32_e32 v182, 16, v240
	v_and_b32_e32 v183, 0xffff0000, v240
	v_lshlrev_b32_e32 v240, 16, v241
	v_and_b32_e32 v241, 0xffff0000, v241
	v_lshlrev_b32_e32 v238, 16, v242
	v_and_b32_e32 v239, 0xffff0000, v242
	v_lshlrev_b32_e32 v242, 16, v243
	v_and_b32_e32 v243, 0xffff0000, v243
	v_pk_fma_f32 v[4:5], v[182:183], s[92:93], v[4:5] op_sel_hi:[1,0,1]
	v_pk_fma_f32 v[6:7], v[240:241], s[92:93], v[6:7] op_sel_hi:[1,0,1]
	v_pk_fma_f32 v[0:1], v[238:239], s[92:93], v[0:1] op_sel_hi:[1,0,1]
	v_pk_fma_f32 v[2:3], v[242:243], s[92:93], v[2:3] op_sel_hi:[1,0,1]
	v_cvt_pk_bf16_f32 v4, v4, v5
	v_cvt_pk_bf16_f32 v5, v6, v7
	v_cvt_pk_bf16_f32 v6, v0, v1
	v_cvt_pk_bf16_f32 v7, v2, v3
	global_store_dwordx4 v139, v[4:7], s[10:11] offset:256
	s_andn2_b64 vcc, exec, s[12:13]
	s_waitcnt vmcnt(22)
	s_cbranch_vccz .LBB0_820
	s_branch .Lseam_res_dn

	.amdhsa_kernel _Z9yoco_mega6Params
		.amdhsa_group_segment_fixed_size 0
		.amdhsa_private_segment_fixed_size 0
		.amdhsa_kernarg_size 368
		.amdhsa_user_sgpr_count 2
		.amdhsa_user_sgpr_dispatch_ptr 0
		.amdhsa_user_sgpr_queue_ptr 0
		.amdhsa_user_sgpr_kernarg_segment_ptr 1
		.amdhsa_user_sgpr_dispatch_id 0
		.amdhsa_user_sgpr_kernarg_preload_length 0
		.amdhsa_user_sgpr_kernarg_preload_offset 0
		.amdhsa_user_sgpr_private_segment_size 0
		.amdhsa_uses_dynamic_stack 0
		.amdhsa_enable_private_segment 0
		.amdhsa_system_sgpr_workgroup_id_x 1
		.amdhsa_system_sgpr_workgroup_id_y 0
		.amdhsa_system_sgpr_workgroup_id_z 0
		.amdhsa_system_sgpr_workgroup_info 0
		.amdhsa_system_vgpr_workitem_id 2
		.amdhsa_next_free_vgpr 256
		.amdhsa_next_free_sgpr 98
		.amdhsa_accum_offset 256
		.amdhsa_reserve_vcc 1
		.amdhsa_float_round_mode_32 0
		.amdhsa_float_round_mode_16_64 0
		.amdhsa_float_denorm_mode_32 3
		.amdhsa_float_denorm_mode_16_64 3
		.amdhsa_dx10_clamp 1
		.amdhsa_ieee_mode 1
		.amdhsa_fp16_overflow 0
		.amdhsa_tg_split 0
		.amdhsa_exception_fp_ieee_invalid_op 0
		.amdhsa_exception_fp_denorm_src 0
		.amdhsa_exception_fp_ieee_div_zero 0
		.amdhsa_exception_fp_ieee_overflow 0
		.amdhsa_exception_fp_ieee_underflow 0
		.amdhsa_exception_fp_ieee_inexact 0
		.amdhsa_exception_int_div_zero 0
	.end_amdhsa_kernel

amdhsa.kernels:
  - .agpr_count:     0
    .args:
      - .offset:         0
        .size:           112
        .value_kind:     by_value
      - .offset:         112
        .size:           4
        .value_kind:     hidden_block_count_x
      - .offset:         116
        .size:           4
        .value_kind:     hidden_block_count_y
      - .offset:         120
        .size:           4
        .value_kind:     hidden_block_count_z
      - .offset:         124
        .size:           2
        .value_kind:     hidden_group_size_x
      - .offset:         126
        .size:           2
        .value_kind:     hidden_group_size_y
      - .offset:         128
        .size:           2
        .value_kind:     hidden_group_size_z
      - .offset:         130
        .size:           2
        .value_kind:     hidden_remainder_x
      - .offset:         132
        .size:           2
        .value_kind:     hidden_remainder_y
      - .offset:         134
        .size:           2
        .value_kind:     hidden_remainder_z
      - .offset:         152
        .size:           8
        .value_kind:     hidden_global_offset_x
      - .offset:         160
        .size:           8
        .value_kind:     hidden_global_offset_y
      - .offset:         168
        .size:           8
        .value_kind:     hidden_global_offset_z
      - .offset:         176
        .size:           2
        .value_kind:     hidden_grid_dims
      - .offset:         200
        .size:           8
        .value_kind:     hidden_multigrid_sync_arg
      - .offset:         232
        .size:           4
        .value_kind:     hidden_dynamic_lds_size
    .group_segment_fixed_size: 0
    .kernarg_segment_align: 8
    .kernarg_segment_size: 368
    .language:       OpenCL C
    .language_version:
      - 2
      - 0
    .max_flat_workgroup_size: 512
    .name:           _Z9yoco_mega6Params
    .private_segment_fixed_size: 0
    .sgpr_count:     104
    .sgpr_spill_count: 104
    .symbol:         _Z9yoco_mega6Params.kd
    .uniform_work_group_size: 1
    .uses_dynamic_stack: false
    .vgpr_count:     256
    .vgpr_spill_count: 0
    .wavefront_size: 64
